# BO + same operand-sharing pair order in the in-place MFMA runs of the four sliver K-loops
# speedup vs baseline: 1.0032x; 1.0006x over previous
; #define PG8_STAGE(bufoff, gbase, voff) do { _Pragma("unroll") for (int _i = 0; _i < 2; ++_i) \
;         __builtin_amdgcn_global_load_lds((const unsigned*)((const char*)(gbase) + (size_t)_i * qstep + (voff)[0]), (PG8_LAS unsigned*)(lds + (bufoff) + ldsw + _i * 8192), 16, 0, 0); } while (0)
; #define PG8_LDA(dst, b, h) do { _Pragma("unroll") for (int m = 0; m < 4; ++m) _Pragma("unroll") for (int k = 0; k < 2; ++k) dst[m][k] = *(const PG8_LAS bf16x8*)(lds + PG8_SA(b, h) + aoff + m * 2048 + k * 1024); } while (0)
; #define PG8_LDB(dst, b, h) do { _Pragma("unroll") for (int n = 0; n < 2; ++n) _Pragma("unroll") for (int k = 0; k < 2; ++k) dst[n][k] = *(const PG8_LAS bf16x8*)(lds + PG8_SB(b, h) + boff + n * 2048 + k * 1024); } while (0)
; #define PG8_WAIT_V89() do { if constexpr (SLIVER) PG8_WAIT_V(9); else PG8_WAIT_V(8); } while (0)
; #define PG8_WAIT_L(n) asm volatile("s_waitcnt lgkmcnt(" #n ")" ::: "memory")
; template <class Epi, class Sched, bool ALIGN_EPI = false, bool SP2 = false, bool SLIVER = false>
; __device__ __forceinline__ void gemm_phase(PG8_LAS unsigned char* lds, const Gemm g, const Sched& S, const Epi& E) {
;     ...
;         const bool has_next = S.next(ui + 1, nxt);
;         const char* nA = has_next ? (const char*)g.A + (size_t)nxt.pm * tstep + Epi::k0(nxt.seg) * 2 : cA; const char* nB = has_next ? (const char*)g.Bt + (size_t)nxt.pn * tstep + Epi::k0(nxt.seg) * 2 : cB;
;         const char* nS = has_next ? (const char*)g.A + (size_t)S.srow0 * K * 2 + (size_t)nxt.pm * sstep + Epi::k0(nxt.seg) * 2 : cS;
;         for (int t = 0; t < nt; t += 2) {
;             const bool last = (t == nt - 2);
;             const char* a1 = cA + (size_t)(t + 1) * kstep;
;             const char* a2 = last ? nA : cA + (size_t)(t + 2) * kstep; const char* b2 = last ? nB : cB + (size_t)(t + 2) * kstep;
;             const char* a3 = a2 + kstep; const char* b3 = b2 + kstep;
;             const char* s1 = cS + (size_t)(t + 1) * kstep; const char* s2 = last ? nS : cS + (size_t)(t + 2) * kstep;
;             if (last && has_next) S.a_ready(nxt);
;             if constexpr (SP2) {
;             PG8_LDB(B0, 0, 0); PG8_LDB(B1, 0, 1); PG8_SCHED; PG8_LDA(At, 0, 0); PG8_STAGE(PG8_SA(1, 1), a1 + hstep, voffA); PG8_STAGE_S(1, s1);
;             PG8_WAIT_V89(); PG8_WAIT_L(0); PG8_BAR; PG8_MMA(0, 0, At, B0); PG8_MMA(0, 1, At, B1); PG8_BAR; PG8_SCHED;
.LBB0_498:
	s_cmp_eq_u32 s66, s80
	s_cselect_b64 s[86:87], -1, 0
	s_add_u32 s40, s16, s80
	s_addc_u32 s41, s17, s81
	s_add_u32 s68, s40, 0x100
	s_addc_u32 s69, s41, 0
	s_and_b64 s[40:41], s[86:87], exec
	s_cselect_b32 s41, s55, s69
	s_cselect_b32 s40, s54, s68
	s_add_u32 s76, s12, s80
	s_addc_u32 s77, s13, s81
	s_add_i32 s78, 0, 0x10000
	s_and_b64 s[68:69], s[86:87], exec
	v_add_u32_e32 v138, s78, v239
	s_cselect_b32 s69, s83, s77
	s_cselect_b32 s68, s82, s76
	s_add_i32 s76, 0, 0x14000
	ds_read_b128 v[146:149], v138
	ds_read_b128 v[150:153], v138 offset:1024
	ds_read_b128 v[154:157], v138 offset:2048
	ds_read_b128 v[158:161], v138 offset:3072
	v_add_u32_e32 v138, s76, v239
	ds_read_b128 v[166:169], v138
	ds_read_b128 v[170:173], v138 offset:1024
	ds_read_b128 v[174:177], v138 offset:2048
	ds_read_b128 v[162:165], v138 offset:3072
	v_lshl_add_u64 v[208:209], v[188:189], 0, s[80:81]
	v_lshl_add_u64 v[224:225], v[208:209], 0, s[34:35]
	s_add_i32 m0, s96, 0xc000
	s_mov_b64 s[88:89], 0x120080
	ds_read_b128 v[138:141], v242
	ds_read_b128 v[142:145], v242 offset:1024
	ds_read_b128 v[180:183], v242 offset:2048
	ds_read_b128 v[184:187], v242 offset:3072
	ds_read_b128 v[192:195], v242 offset:4096
	ds_read_b128 v[196:199], v242 offset:5120
	ds_read_b128 v[200:203], v242 offset:6144
	ds_read_b128 v[220:223], v242 offset:7168
	global_load_lds_dwordx4 v[224:225], off
	v_lshl_add_u64 v[208:209], v[208:209], 0, s[88:89]
	s_add_i32 m0, s96, 0xe000
	s_nop 0
	global_load_lds_dwordx4 v[208:209], off
	v_lshl_add_u64 v[208:209], v[190:191], 0, s[80:81]
	s_add_i32 m0, s94, 0x20800
	s_nop 0
	global_load_lds_dword v[208:209], off
	s_waitcnt vmcnt(9)
	s_waitcnt lgkmcnt(0)
	s_setprio 1
	s_barrier
	v_mfma_f32_16x16x32_bf16 v[134:137], v[146:149], v[138:141], v[134:137]
	v_mfma_f32_16x16x32_bf16 v[134:137], v[150:153], v[142:145], v[134:137]
	v_mfma_f32_16x16x32_bf16 v[130:133], v[158:161], v[142:145], v[130:133]
	v_mfma_f32_16x16x32_bf16 v[130:133], v[154:157], v[138:141], v[130:133]
	v_mfma_f32_16x16x32_bf16 v[122:125], v[154:157], v[180:183], v[122:125]
	v_mfma_f32_16x16x32_bf16 v[122:125], v[158:161], v[184:187], v[122:125]
	v_mfma_f32_16x16x32_bf16 v[126:129], v[150:153], v[184:187], v[126:129]
	v_mfma_f32_16x16x32_bf16 v[126:129], v[146:149], v[180:183], v[126:129]
	v_mfma_f32_16x16x32_bf16 v[118:121], v[146:149], v[192:195], v[118:121]
	v_mfma_f32_16x16x32_bf16 v[118:121], v[150:153], v[196:199], v[118:121]
	v_mfma_f32_16x16x32_bf16 v[114:117], v[158:161], v[196:199], v[114:117]
	v_mfma_f32_16x16x32_bf16 v[114:117], v[154:157], v[192:195], v[114:117]
	v_mfma_f32_16x16x32_bf16 v[106:109], v[154:157], v[200:203], v[106:109]
	v_mfma_f32_16x16x32_bf16 v[106:109], v[158:161], v[220:223], v[106:109]
	v_mfma_f32_16x16x32_bf16 v[110:113], v[150:153], v[220:223], v[110:113]
	v_mfma_f32_16x16x32_bf16 v[110:113], v[146:149], v[200:203], v[110:113]
	s_setprio 0
	s_setprio 1
	v_mfma_f32_16x16x32_bf16 v[102:105], v[166:169], v[138:141], v[102:105]
	v_mfma_f32_16x16x32_bf16 v[102:105], v[170:173], v[142:145], v[102:105]
	v_mfma_f32_16x16x32_bf16 v[98:101], v[162:165], v[142:145], v[98:101]
	v_mfma_f32_16x16x32_bf16 v[98:101], v[174:177], v[138:141], v[98:101]
	v_mfma_f32_16x16x32_bf16 v[86:89], v[174:177], v[180:183], v[86:89]
	v_mfma_f32_16x16x32_bf16 v[86:89], v[162:165], v[184:187], v[86:89]
	v_mfma_f32_16x16x32_bf16 v[90:93], v[170:173], v[184:187], v[90:93]
	v_mfma_f32_16x16x32_bf16 v[90:93], v[166:169], v[180:183], v[90:93]
	v_mfma_f32_16x16x32_bf16 v[78:81], v[166:169], v[192:195], v[78:81]
	v_mfma_f32_16x16x32_bf16 v[78:81], v[170:173], v[196:199], v[78:81]
	v_mfma_f32_16x16x32_bf16 v[74:77], v[162:165], v[196:199], v[74:77]
	v_mfma_f32_16x16x32_bf16 v[74:77], v[174:177], v[192:195], v[74:77]
	v_mfma_f32_16x16x32_bf16 v[66:69], v[174:177], v[200:203], v[66:69]
	v_mfma_f32_16x16x32_bf16 v[66:69], v[162:165], v[220:223], v[66:69]
	v_mfma_f32_16x16x32_bf16 v[70:73], v[170:173], v[220:223], v[70:73]
	v_mfma_f32_16x16x32_bf16 v[70:73], v[166:169], v[200:203], v[70:73]
	s_barrier
; #define PG8_SB(B) __builtin_amdgcn_rcpf(1.f + expneg(B))
; #define PG8_SB(B) __builtin_amdgcn_rcpf(1.f + expneg(B))
; #define PG8_STAGE(bufoff, gbase, voff) do { _Pragma("unroll") for (int _i = 0; _i < 2; ++_i) \
;         __builtin_amdgcn_global_load_lds((const unsigned*)((const char*)(gbase) + (size_t)_i * qstep + (voff)[0]), (PG8_LAS unsigned*)(lds + (bufoff) + ldsw + _i * 8192), 16, 0, 0); } while (0)
; #define PG8_LDA(dst, b, h) do { _Pragma("unroll") for (int m = 0; m < 4; ++m) _Pragma("unroll") for (int k = 0; k < 2; ++k) dst[m][k] = *(const PG8_LAS bf16x8*)(lds + PG8_SA(b, h) + aoff + m * 2048 + k * 1024); } while (0)
; #define PG8_MMA(ai, bj, At, Bt) do { __builtin_amdgcn_s_setprio(1); _Pragma("unroll") for (int m = 0; m < 4; ++m) _Pragma("unroll") for (int n = 0; n < 2; ++n) _Pragma("unroll") for (int k = 0; k < 2; ++k) \
;         acc[ai][bj][m][n] = __builtin_amdgcn_mfma_f32_16x16x32_bf16(Bt[n][k], At[m][k], acc[ai][bj][m][n], 0, 0, 0); __builtin_amdgcn_s_setprio(0); } while (0)
; #define PG8_WAIT_V89() do { if constexpr (SLIVER) PG8_WAIT_V(9); else PG8_WAIT_V(8); } while (0)
; #define PG8_LDS_S(b) do { if constexpr (SLIVER) { Sf[0] = *(const PG8_LAS bf16x8*)(lds + STAGE_BYTES + (b) * 2048 + soff0); Sf[1] = *(const PG8_LAS bf16x8*)(lds + STAGE_BYTES + (b) * 2048 + (soff0 ^ 64)); } } while (0)
; #define PG8_WAIT_L(n) asm volatile("s_waitcnt lgkmcnt(" #n ")" ::: "memory")
; #define PG8_BAR __builtin_amdgcn_s_barrier()
; #define PG8_SCHED __builtin_amdgcn_sched_barrier(0)
; template <class Epi, class Sched, bool ALIGN_EPI = false, bool SP2 = false, bool SLIVER = false>
; __device__ __forceinline__ void gemm_phase(PG8_LAS unsigned char* lds, const Gemm g, const Sched& S, const Epi& E) {
;     ...
;             PG8_LDA(At, 0, 1); PG8_LDS_S(0); PG8_STAGE(PG8_SB(0, 0), b2, voffB); PG8_STAGE(PG8_SB(0, 1), b2 + hstep, voffB); PG8_STAGE(PG8_SA(0, 0), a2, voffA);
;             PG8_WAIT_V89(); PG8_WAIT_L(0); PG8_BAR; PG8_MMA(1, 0, At, B0); PG8_MMA(1, 1, At, B1); PG8_MMA_S(); PG8_BAR; PG8_SCHED;
	s_setprio 0
	s_add_i32 s77, 0, 0x20000
	v_lshl_add_u64 v[192:193], s[68:69], 0, v[212:213]
	s_add_i32 s68, s78, s95
	v_add_u32_e32 v178, s77, v240
	v_add_u32_e32 v184, s77, v241
	s_mov_b32 m0, s68
	s_mov_b64 s[88:89], 0x60000
	ds_read_b128 v[138:141], v242 offset:16384
	ds_read_b128 v[142:145], v242 offset:17408
	ds_read_b128 v[196:199], v242 offset:18432
	ds_read_b128 v[200:203], v242 offset:19456
	ds_read_b128 v[220:223], v242 offset:20480
	ds_read_b128 v[224:227], v242 offset:21504
	ds_read_b128 v[228:231], v242 offset:22528
	ds_read_b128 v[232:235], v242 offset:23552
	ds_read_b128 v[180:183], v178
	ds_read_b128 v[184:187], v184
	global_load_lds_dwordx4 v[192:193], off
	v_lshl_add_u64 v[194:195], v[192:193], 0, s[88:89]
	s_add_i32 m0, s68, 0x2000
	s_add_i32 s68, s76, s95
	global_load_lds_dwordx4 v[194:195], off
	v_lshl_add_u64 v[194:195], v[192:193], 0, s[24:25]
	s_mov_b32 m0, s68
	s_nop 0
	global_load_lds_dwordx4 v[194:195], off
	v_lshl_add_u64 v[194:195], v[192:193], 0, s[14:15]
	s_add_i32 m0, s68, 0x2000
	s_nop 0
	global_load_lds_dwordx4 v[194:195], off
	v_lshl_add_u64 v[194:195], s[40:41], 0, v[210:211]
	s_mov_b32 m0, s96
	v_lshl_add_u64 v[208:209], v[194:195], 0, s[88:89]
	global_load_lds_dwordx4 v[194:195], off
	s_mov_b32 m0, s19
	s_nop 0
	global_load_lds_dwordx4 v[208:209], off
	s_waitcnt vmcnt(9)
	s_waitcnt lgkmcnt(0)
	s_setprio 1
	s_barrier
	v_mfma_f32_16x16x32_bf16 v[62:65], v[146:149], v[138:141], v[62:65]
	v_mfma_f32_16x16x32_bf16 v[62:65], v[150:153], v[142:145], v[62:65]
	v_mfma_f32_16x16x32_bf16 v[58:61], v[158:161], v[142:145], v[58:61]
	v_mfma_f32_16x16x32_bf16 v[58:61], v[154:157], v[138:141], v[58:61]
	v_mfma_f32_16x16x32_bf16 v[50:53], v[154:157], v[196:199], v[50:53]
	v_mfma_f32_16x16x32_bf16 v[50:53], v[158:161], v[200:203], v[50:53]
	v_mfma_f32_16x16x32_bf16 v[54:57], v[150:153], v[200:203], v[54:57]
	v_mfma_f32_16x16x32_bf16 v[54:57], v[146:149], v[196:199], v[54:57]
	v_mfma_f32_16x16x32_bf16 v[46:49], v[146:149], v[220:223], v[46:49]
	v_mfma_f32_16x16x32_bf16 v[46:49], v[150:153], v[224:227], v[46:49]
	v_mfma_f32_16x16x32_bf16 v[42:45], v[158:161], v[224:227], v[42:45]
	v_mfma_f32_16x16x32_bf16 v[42:45], v[154:157], v[220:223], v[42:45]
	v_mfma_f32_16x16x32_bf16 v[34:37], v[154:157], v[228:231], v[34:37]
	v_mfma_f32_16x16x32_bf16 v[34:37], v[158:161], v[232:235], v[34:37]
	v_mfma_f32_16x16x32_bf16 v[38:41], v[150:153], v[232:235], v[38:41]
	v_mfma_f32_16x16x32_bf16 v[38:41], v[146:149], v[228:231], v[38:41]
	s_setprio 0
	s_setprio 1
	v_mfma_f32_16x16x32_bf16 v[30:33], v[166:169], v[138:141], v[30:33]
	v_mfma_f32_16x16x32_bf16 v[30:33], v[170:173], v[142:145], v[30:33]
	v_mfma_f32_16x16x32_bf16 v[26:29], v[162:165], v[142:145], v[26:29]
	v_mfma_f32_16x16x32_bf16 v[26:29], v[174:177], v[138:141], v[26:29]
	v_mfma_f32_16x16x32_bf16 v[18:21], v[174:177], v[196:199], v[18:21]
	v_mfma_f32_16x16x32_bf16 v[18:21], v[162:165], v[200:203], v[18:21]
	v_mfma_f32_16x16x32_bf16 v[22:25], v[170:173], v[200:203], v[22:25]
	v_mfma_f32_16x16x32_bf16 v[22:25], v[166:169], v[196:199], v[22:25]
	v_mfma_f32_16x16x32_bf16 v[14:17], v[166:169], v[220:223], v[14:17]
	v_mfma_f32_16x16x32_bf16 v[14:17], v[170:173], v[224:227], v[14:17]
	v_mfma_f32_16x16x32_bf16 v[10:13], v[162:165], v[224:227], v[10:13]
	v_mfma_f32_16x16x32_bf16 v[10:13], v[174:177], v[220:223], v[10:13]
	v_mfma_f32_16x16x32_bf16 v[2:5], v[174:177], v[228:231], v[2:5]
	v_mfma_f32_16x16x32_bf16 v[2:5], v[162:165], v[232:235], v[2:5]
	v_mfma_f32_16x16x32_bf16 v[6:9], v[170:173], v[232:235], v[6:9]
	v_mfma_f32_16x16x32_bf16 v[6:9], v[166:169], v[228:231], v[6:9]
	s_setprio 0
	s_setprio 1
	s_and_b64 vcc, exec, s[52:53]
	s_cbranch_vccz .Lslv_b0
	v_mfma_f32_16x16x32_bf16 v[138:141], v[166:169], v[180:183], v[82:85]
	v_mfma_f32_16x16x32_bf16 v[142:145], v[174:177], v[180:183], v[94:97]
	v_mfma_f32_16x16x32_bf16 v[138:141], v[170:173], v[184:187], v[138:141]
	v_mfma_f32_16x16x32_bf16 v[142:145], v[162:165], v[184:187], v[142:145]
	s_branch .LBB0_502

; #define PG8_STAGE(bufoff, gbase, voff) do { _Pragma("unroll") for (int _i = 0; _i < 2; ++_i) \
;         __builtin_amdgcn_global_load_lds((const unsigned*)((const char*)(gbase) + (size_t)_i * qstep + (voff)[0]), (PG8_LAS unsigned*)(lds + (bufoff) + ldsw + _i * 8192), 16, 0, 0); } while (0)
; #define PG8_LDA(dst, b, h) do { _Pragma("unroll") for (int m = 0; m < 4; ++m) _Pragma("unroll") for (int k = 0; k < 2; ++k) dst[m][k] = *(const PG8_LAS bf16x8*)(lds + PG8_SA(b, h) + aoff + m * 2048 + k * 1024); } while (0)
; #define PG8_LDB(dst, b, h) do { _Pragma("unroll") for (int n = 0; n < 2; ++n) _Pragma("unroll") for (int k = 0; k < 2; ++k) dst[n][k] = *(const PG8_LAS bf16x8*)(lds + PG8_SB(b, h) + boff + n * 2048 + k * 1024); } while (0)
; #define PG8_MMA(ai, bj, At, Bt) do { __builtin_amdgcn_s_setprio(1); _Pragma("unroll") for (int m = 0; m < 4; ++m) _Pragma("unroll") for (int n = 0; n < 2; ++n) _Pragma("unroll") for (int k = 0; k < 2; ++k) \
;         acc[ai][bj][m][n] = __builtin_amdgcn_mfma_f32_16x16x32_bf16(Bt[n][k], At[m][k], acc[ai][bj][m][n], 0, 0, 0); __builtin_amdgcn_s_setprio(0); } while (0)
; #define PG8_WAIT_V89() do { if constexpr (SLIVER) PG8_WAIT_V(9); else PG8_WAIT_V(8); } while (0)
; #define PG8_STAGE_S(b, gbase) do { if constexpr (SLIVER) __builtin_amdgcn_global_load_lds((const unsigned*)((const char*)(gbase) + voffS), (PG8_LAS unsigned*)(lds + STAGE_BYTES + (b) * 2048 + wid * 256), 4, 0, 0); } while (0)
; #define PG8_WAIT_L(n) asm volatile("s_waitcnt lgkmcnt(" #n ")" ::: "memory")
; #define PG8_BAR __builtin_amdgcn_s_barrier()
; #define PG8_SCHED __builtin_amdgcn_sched_barrier(0)
; template <class Epi, class Sched, bool ALIGN_EPI = false, bool SP2 = false, bool SLIVER = false>
; __device__ __forceinline__ void gemm_phase(PG8_LAS unsigned char* lds, const Gemm g, const Sched& S, const Epi& E) {
;     ...
;             PG8_LDB(B0, 1, 0); PG8_LDB(B1, 1, 1); PG8_SCHED; PG8_LDA(At, 1, 0); PG8_STAGE(PG8_SA(0, 1), a2 + hstep, voffA); PG8_STAGE_S(0, s2);
;             PG8_WAIT_V89(); PG8_WAIT_L(0); PG8_BAR; PG8_MMA(0, 0, At, B0); PG8_MMA(0, 1, At, B1); PG8_BAR; PG8_SCHED;
.LBB0_502:
	s_barrier
	s_setprio 0
	s_add_u32 s68, s62, s80
	s_addc_u32 s69, s63, s81
	s_add_u32 s76, s68, 0x100
	s_addc_u32 s77, s69, 0
	s_and_b64 s[68:69], s[86:87], exec
	s_cselect_b32 s69, s85, s77
	s_cselect_b32 s68, s84, s76
	s_add_i32 s76, 0, 0x18000
	v_add_u32_e32 v82, s76, v239
	s_add_i32 s77, 0, 0x1c000
	ds_read_b128 v[146:149], v82
	ds_read_b128 v[150:153], v82 offset:1024
	ds_read_b128 v[154:157], v82 offset:2048
	ds_read_b128 v[158:161], v82 offset:3072
	v_add_u32_e32 v82, s77, v239
	ds_read_b128 v[166:169], v82
	ds_read_b128 v[170:173], v82 offset:1024
	ds_read_b128 v[174:177], v82 offset:2048
	ds_read_b128 v[162:165], v82 offset:3072
	s_mov_b32 m0, s91
	v_lshl_add_u64 v[208:209], v[194:195], 0, s[24:25]
	ds_read_b128 v[82:85], v242 offset:32768
	ds_read_b128 v[94:97], v242 offset:33792
	ds_read_b128 v[180:183], v242 offset:34816
	ds_read_b128 v[184:187], v242 offset:35840
	ds_read_b128 v[196:199], v242 offset:36864
	ds_read_b128 v[200:203], v242 offset:37888
	ds_read_b128 v[220:223], v242 offset:38912
	ds_read_b128 v[224:227], v242 offset:39936
	global_load_lds_dwordx4 v[208:209], off
	v_lshl_add_u64 v[208:209], v[194:195], 0, s[14:15]
	s_mov_b32 m0, s92
	s_nop 0
	global_load_lds_dwordx4 v[208:209], off
	v_lshl_add_u64 v[208:209], s[68:69], 0, v[214:215]
	s_mov_b32 m0, s93
	s_nop 0
	global_load_lds_dword v[208:209], off
	s_waitcnt vmcnt(9)
	s_waitcnt lgkmcnt(0)
	s_setprio 1
	s_barrier
	v_mfma_f32_16x16x32_bf16 v[134:137], v[146:149], v[82:85], v[134:137]
	v_mfma_f32_16x16x32_bf16 v[134:137], v[150:153], v[94:97], v[134:137]
	v_mfma_f32_16x16x32_bf16 v[130:133], v[158:161], v[94:97], v[130:133]
	v_mfma_f32_16x16x32_bf16 v[130:133], v[154:157], v[82:85], v[130:133]
	v_mfma_f32_16x16x32_bf16 v[122:125], v[154:157], v[180:183], v[122:125]
	v_mfma_f32_16x16x32_bf16 v[122:125], v[158:161], v[184:187], v[122:125]
	v_mfma_f32_16x16x32_bf16 v[126:129], v[150:153], v[184:187], v[126:129]
	v_mfma_f32_16x16x32_bf16 v[126:129], v[146:149], v[180:183], v[126:129]
	v_mfma_f32_16x16x32_bf16 v[118:121], v[146:149], v[196:199], v[118:121]
	v_mfma_f32_16x16x32_bf16 v[118:121], v[150:153], v[200:203], v[118:121]
	v_mfma_f32_16x16x32_bf16 v[114:117], v[158:161], v[200:203], v[114:117]
	v_mfma_f32_16x16x32_bf16 v[114:117], v[154:157], v[196:199], v[114:117]
	v_mfma_f32_16x16x32_bf16 v[106:109], v[154:157], v[220:223], v[106:109]
	v_mfma_f32_16x16x32_bf16 v[106:109], v[158:161], v[224:227], v[106:109]
	v_mfma_f32_16x16x32_bf16 v[110:113], v[150:153], v[224:227], v[110:113]
	v_mfma_f32_16x16x32_bf16 v[110:113], v[146:149], v[220:223], v[110:113]
	s_setprio 0
	s_setprio 1
	v_mfma_f32_16x16x32_bf16 v[102:105], v[166:169], v[82:85], v[102:105]
	v_mfma_f32_16x16x32_bf16 v[102:105], v[170:173], v[94:97], v[102:105]
	v_mfma_f32_16x16x32_bf16 v[82:85], v[174:177], v[82:85], v[98:101]
	v_mfma_f32_16x16x32_bf16 v[98:101], v[162:165], v[94:97], v[82:85]
	v_mfma_f32_16x16x32_bf16 v[82:85], v[166:169], v[180:183], v[90:93]
	v_mfma_f32_16x16x32_bf16 v[90:93], v[170:173], v[184:187], v[82:85]
	v_mfma_f32_16x16x32_bf16 v[82:85], v[174:177], v[180:183], v[86:89]
	v_mfma_f32_16x16x32_bf16 v[86:89], v[162:165], v[184:187], v[82:85]
	v_mfma_f32_16x16x32_bf16 v[78:81], v[166:169], v[196:199], v[78:81]
	v_mfma_f32_16x16x32_bf16 v[78:81], v[170:173], v[200:203], v[78:81]
	v_mfma_f32_16x16x32_bf16 v[74:77], v[174:177], v[196:199], v[74:77]
	v_mfma_f32_16x16x32_bf16 v[74:77], v[162:165], v[200:203], v[74:77]
	v_mfma_f32_16x16x32_bf16 v[70:73], v[166:169], v[220:223], v[70:73]
	v_mfma_f32_16x16x32_bf16 v[70:73], v[170:173], v[224:227], v[70:73]
	v_mfma_f32_16x16x32_bf16 v[66:69], v[174:177], v[220:223], v[66:69]
	v_mfma_f32_16x16x32_bf16 v[66:69], v[162:165], v[224:227], v[66:69]
	s_barrier
; #define PG8_SB(B) __builtin_amdgcn_rcpf(1.f + expneg(B))
; #define PG8_SB(B) __builtin_amdgcn_rcpf(1.f + expneg(B))
; #define PG8_STAGE(bufoff, gbase, voff) do { _Pragma("unroll") for (int _i = 0; _i < 2; ++_i) \
;         __builtin_amdgcn_global_load_lds((const unsigned*)((const char*)(gbase) + (size_t)_i * qstep + (voff)[0]), (PG8_LAS unsigned*)(lds + (bufoff) + ldsw + _i * 8192), 16, 0, 0); } while (0)
; #define PG8_LDA(dst, b, h) do { _Pragma("unroll") for (int m = 0; m < 4; ++m) _Pragma("unroll") for (int k = 0; k < 2; ++k) dst[m][k] = *(const PG8_LAS bf16x8*)(lds + PG8_SA(b, h) + aoff + m * 2048 + k * 1024); } while (0)
; #define PG8_MMA(ai, bj, At, Bt) do { __builtin_amdgcn_s_setprio(1); _Pragma("unroll") for (int m = 0; m < 4; ++m) _Pragma("unroll") for (int n = 0; n < 2; ++n) _Pragma("unroll") for (int k = 0; k < 2; ++k) \
;         acc[ai][bj][m][n] = __builtin_amdgcn_mfma_f32_16x16x32_bf16(Bt[n][k], At[m][k], acc[ai][bj][m][n], 0, 0, 0); __builtin_amdgcn_s_setprio(0); } while (0)
; #define PG8_WAIT_V89() do { if constexpr (SLIVER) PG8_WAIT_V(9); else PG8_WAIT_V(8); } while (0)
; #define PG8_LDS_S(b) do { if constexpr (SLIVER) { Sf[0] = *(const PG8_LAS bf16x8*)(lds + STAGE_BYTES + (b) * 2048 + soff0); Sf[1] = *(const PG8_LAS bf16x8*)(lds + STAGE_BYTES + (b) * 2048 + (soff0 ^ 64)); } } while (0)
; #define PG8_WAIT_L(n) asm volatile("s_waitcnt lgkmcnt(" #n ")" ::: "memory")
; #define PG8_BAR __builtin_amdgcn_s_barrier()
; #define PG8_SCHED __builtin_amdgcn_sched_barrier(0)
; template <class Epi, class Sched, bool ALIGN_EPI = false, bool SP2 = false, bool SLIVER = false>
; __device__ __forceinline__ void gemm_phase(PG8_LAS unsigned char* lds, const Gemm g, const Sched& S, const Epi& E) {
;     ...
;             PG8_LDA(At, 1, 1); PG8_LDS_S(1); PG8_STAGE(PG8_SB(1, 0), b3, voffB); PG8_STAGE(PG8_SB(1, 1), b3 + hstep, voffB); PG8_STAGE(PG8_SA(1, 0), a3, voffA);
;             PG8_WAIT_V89(); PG8_WAIT_L(0); PG8_BAR; PG8_MMA(1, 0, At, B0); PG8_MMA(1, 1, At, B1); PG8_MMA_S(); PG8_BAR; PG8_SCHED;
	s_setprio 0
	s_add_i32 s68, 0, 0x20800
	v_add_u32_e32 v178, s68, v240
	v_add_u32_e32 v184, s68, v241
	s_add_i32 s68, s76, s95
	v_lshl_add_u64 v[208:209], v[192:193], 0, s[26:27]
	s_mov_b32 m0, s68
	ds_read_b128 v[82:85], v242 offset:49152
	ds_read_b128 v[94:97], v242 offset:50176
	ds_read_b128 v[196:199], v242 offset:51200
	ds_read_b128 v[200:203], v242 offset:52224
	ds_read_b128 v[220:223], v242 offset:53248
	ds_read_b128 v[224:227], v242 offset:54272
	ds_read_b128 v[228:231], v242 offset:55296
	ds_read_b128 v[232:235], v242 offset:56320
	ds_read_b128 v[180:183], v178
	ds_read_b128 v[184:187], v184
	global_load_lds_dwordx4 v[208:209], off
	v_lshl_add_u64 v[208:209], v[192:193], 0, s[72:73]
	s_add_i32 m0, s68, 0x2000
	s_add_i32 s68, s77, s95
	global_load_lds_dwordx4 v[208:209], off
	v_lshl_add_u64 v[208:209], v[192:193], 0, s[34:35]
	s_mov_b32 m0, s68
	s_mov_b64 s[76:77], 0x120080
	global_load_lds_dwordx4 v[208:209], off
	v_lshl_add_u64 v[192:193], v[192:193], 0, s[76:77]
	s_add_i32 m0, s68, 0x2000
	s_nop 0
	global_load_lds_dwordx4 v[192:193], off
	v_lshl_add_u64 v[192:193], v[194:195], 0, s[26:27]
	s_mov_b32 m0, s97
	s_nop 0
	global_load_lds_dwordx4 v[192:193], off
	v_lshl_add_u64 v[192:193], v[194:195], 0, s[72:73]
	s_mov_b32 m0, s18
	s_nop 0
	global_load_lds_dwordx4 v[192:193], off
	s_waitcnt vmcnt(9)
	s_waitcnt lgkmcnt(0)
	s_setprio 1
	s_barrier
	v_mfma_f32_16x16x32_bf16 v[62:65], v[146:149], v[82:85], v[62:65]
	v_mfma_f32_16x16x32_bf16 v[62:65], v[150:153], v[94:97], v[62:65]
	v_mfma_f32_16x16x32_bf16 v[58:61], v[158:161], v[94:97], v[58:61]
	v_mfma_f32_16x16x32_bf16 v[58:61], v[154:157], v[82:85], v[58:61]
	v_mfma_f32_16x16x32_bf16 v[50:53], v[154:157], v[196:199], v[50:53]
	v_mfma_f32_16x16x32_bf16 v[50:53], v[158:161], v[200:203], v[50:53]
	v_mfma_f32_16x16x32_bf16 v[54:57], v[150:153], v[200:203], v[54:57]
	v_mfma_f32_16x16x32_bf16 v[54:57], v[146:149], v[196:199], v[54:57]
	v_mfma_f32_16x16x32_bf16 v[46:49], v[146:149], v[220:223], v[46:49]
	v_mfma_f32_16x16x32_bf16 v[46:49], v[150:153], v[224:227], v[46:49]
	v_mfma_f32_16x16x32_bf16 v[42:45], v[158:161], v[224:227], v[42:45]
	v_mfma_f32_16x16x32_bf16 v[42:45], v[154:157], v[220:223], v[42:45]
	v_mfma_f32_16x16x32_bf16 v[34:37], v[154:157], v[228:231], v[34:37]
	v_mfma_f32_16x16x32_bf16 v[34:37], v[158:161], v[232:235], v[34:37]
	v_mfma_f32_16x16x32_bf16 v[38:41], v[150:153], v[232:235], v[38:41]
	v_mfma_f32_16x16x32_bf16 v[38:41], v[146:149], v[228:231], v[38:41]
	s_setprio 0
	s_setprio 1
	v_mfma_f32_16x16x32_bf16 v[30:33], v[166:169], v[82:85], v[30:33]
	v_mfma_f32_16x16x32_bf16 v[30:33], v[170:173], v[94:97], v[30:33]
	v_mfma_f32_16x16x32_bf16 v[26:29], v[162:165], v[94:97], v[26:29]
	v_mfma_f32_16x16x32_bf16 v[26:29], v[174:177], v[82:85], v[26:29]
	v_mfma_f32_16x16x32_bf16 v[18:21], v[174:177], v[196:199], v[18:21]
	v_mfma_f32_16x16x32_bf16 v[18:21], v[162:165], v[200:203], v[18:21]
	v_mfma_f32_16x16x32_bf16 v[22:25], v[170:173], v[200:203], v[22:25]
	v_mfma_f32_16x16x32_bf16 v[22:25], v[166:169], v[196:199], v[22:25]
	v_mfma_f32_16x16x32_bf16 v[14:17], v[166:169], v[220:223], v[14:17]
	v_mfma_f32_16x16x32_bf16 v[14:17], v[170:173], v[224:227], v[14:17]
	v_mfma_f32_16x16x32_bf16 v[10:13], v[162:165], v[224:227], v[10:13]
	v_mfma_f32_16x16x32_bf16 v[10:13], v[174:177], v[220:223], v[10:13]
	v_mfma_f32_16x16x32_bf16 v[2:5], v[174:177], v[228:231], v[2:5]
	v_mfma_f32_16x16x32_bf16 v[2:5], v[162:165], v[232:235], v[2:5]
	v_mfma_f32_16x16x32_bf16 v[6:9], v[170:173], v[232:235], v[6:9]
	v_mfma_f32_16x16x32_bf16 v[6:9], v[166:169], v[228:231], v[6:9]
	s_setprio 0
	s_setprio 1
	s_and_b64 vcc, exec, s[52:53]
	s_cbranch_vccz .Lslv_c0
	v_mfma_f32_16x16x32_bf16 v[82:85], v[166:169], v[180:183], v[138:141]
	v_mfma_f32_16x16x32_bf16 v[94:97], v[174:177], v[180:183], v[142:145]
	v_mfma_f32_16x16x32_bf16 v[82:85], v[170:173], v[184:187], v[82:85]
	v_mfma_f32_16x16x32_bf16 v[94:97], v[162:165], v[184:187], v[94:97]
	s_branch .LBB0_497

; #define PG8_STAGE(bufoff, gbase, voff) do { _Pragma("unroll") for (int _i = 0; _i < 2; ++_i) \
;         __builtin_amdgcn_global_load_lds((const unsigned*)((const char*)(gbase) + (size_t)_i * qstep + (voff)[0]), (PG8_LAS unsigned*)(lds + (bufoff) + ldsw + _i * 8192), 16, 0, 0); } while (0)
; #define PG8_LDA(dst, b, h) do { _Pragma("unroll") for (int m = 0; m < 4; ++m) _Pragma("unroll") for (int k = 0; k < 2; ++k) dst[m][k] = *(const PG8_LAS bf16x8*)(lds + PG8_SA(b, h) + aoff + m * 2048 + k * 1024); } while (0)
; #define PG8_LDB(dst, b, h) do { _Pragma("unroll") for (int n = 0; n < 2; ++n) _Pragma("unroll") for (int k = 0; k < 2; ++k) dst[n][k] = *(const PG8_LAS bf16x8*)(lds + PG8_SB(b, h) + boff + n * 2048 + k * 1024); } while (0)
; #define PG8_WAIT_V89() do { if constexpr (SLIVER) PG8_WAIT_V(9); else PG8_WAIT_V(8); } while (0)
; #define PG8_WAIT_L(n) asm volatile("s_waitcnt lgkmcnt(" #n ")" ::: "memory")
; template <class Epi, class Sched, bool ALIGN_EPI = false, bool SP2 = false, bool SLIVER = false>
; __device__ __forceinline__ void gemm_phase(PG8_LAS unsigned char* lds, const Gemm g, const Sched& S, const Epi& E) {
;     ...
;         const bool has_next = S.next(ui + 1, nxt);
;         const char* nA = has_next ? (const char*)g.A + (size_t)nxt.pm * tstep + Epi::k0(nxt.seg) * 2 : cA; const char* nB = has_next ? (const char*)g.Bt + (size_t)nxt.pn * tstep + Epi::k0(nxt.seg) * 2 : cB;
;         const char* nS = has_next ? (const char*)g.A + (size_t)S.srow0 * K * 2 + (size_t)nxt.pm * sstep + Epi::k0(nxt.seg) * 2 : cS;
;         for (int t = 0; t < nt; t += 2) {
;             const bool last = (t == nt - 2);
;             const char* a1 = cA + (size_t)(t + 1) * kstep;
;             const char* a2 = last ? nA : cA + (size_t)(t + 2) * kstep; const char* b2 = last ? nB : cB + (size_t)(t + 2) * kstep;
;             const char* a3 = a2 + kstep; const char* b3 = b2 + kstep;
;             const char* s1 = cS + (size_t)(t + 1) * kstep; const char* s2 = last ? nS : cS + (size_t)(t + 2) * kstep;
;             if (last && has_next) S.a_ready(nxt);
;             if constexpr (SP2) {
;             PG8_LDB(B0, 0, 0); PG8_LDB(B1, 0, 1); PG8_SCHED; PG8_LDA(At, 0, 0); PG8_STAGE(PG8_SA(1, 1), a1 + hstep, voffA); PG8_STAGE_S(1, s1);
;             PG8_WAIT_V89(); PG8_WAIT_L(0); PG8_BAR; PG8_MMA(0, 0, At, B0); PG8_MMA(0, 1, At, B1); PG8_BAR; PG8_SCHED;
.LBB0_598:
	s_add_u32 s40, s92, s62
	s_addc_u32 s41, s93, s63
	s_add_u32 s77, s40, 0x100
	s_addc_u32 s78, s41, 0
	s_add_u32 s83, s68, s62
	s_addc_u32 s79, s69, s63
	s_add_i32 s96, 0, 0x10000
	s_cmpk_eq_i32 s62, 0xf00
	s_cselect_b64 s[80:81], -1, 0
	s_and_b64 s[40:41], s[80:81], exec
	s_cselect_b32 s41, s12, s78
	s_cselect_b32 s40, s13, s77
	v_add_u32_e32 v138, s96, v212
	s_cselect_b32 s79, s17, s79
	s_cselect_b32 s78, s55, s83
	s_add_i32 s77, 0, 0x14000
	ds_read_b128 v[146:149], v138
	ds_read_b128 v[150:153], v138 offset:1024
	ds_read_b128 v[154:157], v138 offset:2048
	ds_read_b128 v[158:161], v138 offset:3072
	v_add_u32_e32 v138, s77, v212
	ds_read_b128 v[166:169], v138
	ds_read_b128 v[170:173], v138 offset:1024
	ds_read_b128 v[174:177], v138 offset:2048
	ds_read_b128 v[162:165], v138 offset:3072
	v_lshl_add_u64 v[202:203], v[200:201], 0, s[62:63]
	v_lshl_add_u64 v[208:209], v[202:203], 0, s[30:31]
	s_add_i32 m0, s85, 0xc000
	ds_read_b128 v[138:141], v215
	ds_read_b128 v[142:145], v215 offset:1024
	ds_read_b128 v[180:183], v215 offset:2048
	ds_read_b128 v[184:187], v215 offset:3072
	ds_read_b128 v[216:219], v215 offset:4096
	ds_read_b128 v[220:223], v215 offset:5120
	ds_read_b128 v[224:227], v215 offset:6144
	ds_read_b128 v[228:231], v215 offset:7168
	global_load_lds_dwordx4 v[208:209], off
	v_lshl_add_u64 v[202:203], v[202:203], 0, s[34:35]
	s_add_i32 m0, s85, 0xe000
	s_nop 0
	global_load_lds_dwordx4 v[202:203], off
	v_lshl_add_u64 v[202:203], v[198:199], 0, s[62:63]
	s_add_i32 m0, s45, 0x20800
	s_nop 0
	global_load_lds_dword v[202:203], off
	s_waitcnt vmcnt(9)
	s_waitcnt lgkmcnt(0)
	s_setprio 1
	s_barrier
	v_mfma_f32_16x16x32_bf16 v[134:137], v[146:149], v[138:141], v[134:137]
	v_mfma_f32_16x16x32_bf16 v[134:137], v[150:153], v[142:145], v[134:137]
	v_mfma_f32_16x16x32_bf16 v[130:133], v[158:161], v[142:145], v[130:133]
	v_mfma_f32_16x16x32_bf16 v[130:133], v[154:157], v[138:141], v[130:133]
	v_mfma_f32_16x16x32_bf16 v[114:117], v[154:157], v[180:183], v[114:117]
	v_mfma_f32_16x16x32_bf16 v[114:117], v[158:161], v[184:187], v[114:117]
	v_mfma_f32_16x16x32_bf16 v[118:121], v[150:153], v[184:187], v[118:121]
	v_mfma_f32_16x16x32_bf16 v[118:121], v[146:149], v[180:183], v[118:121]
	v_mfma_f32_16x16x32_bf16 v[102:105], v[146:149], v[216:219], v[102:105]
	v_mfma_f32_16x16x32_bf16 v[102:105], v[150:153], v[220:223], v[102:105]
	v_mfma_f32_16x16x32_bf16 v[98:101], v[158:161], v[220:223], v[98:101]
	v_mfma_f32_16x16x32_bf16 v[98:101], v[154:157], v[216:219], v[98:101]
	v_mfma_f32_16x16x32_bf16 v[82:85], v[154:157], v[224:227], v[82:85]
	v_mfma_f32_16x16x32_bf16 v[82:85], v[158:161], v[228:231], v[82:85]
	v_mfma_f32_16x16x32_bf16 v[86:89], v[150:153], v[228:231], v[86:89]
	v_mfma_f32_16x16x32_bf16 v[86:89], v[146:149], v[224:227], v[86:89]
	s_setprio 0
	s_setprio 1
	v_mfma_f32_16x16x32_bf16 v[126:129], v[166:169], v[138:141], v[126:129]
	v_mfma_f32_16x16x32_bf16 v[126:129], v[170:173], v[142:145], v[126:129]
	v_mfma_f32_16x16x32_bf16 v[122:125], v[162:165], v[142:145], v[122:125]
	v_mfma_f32_16x16x32_bf16 v[122:125], v[174:177], v[138:141], v[122:125]
	v_mfma_f32_16x16x32_bf16 v[106:109], v[174:177], v[180:183], v[106:109]
	v_mfma_f32_16x16x32_bf16 v[106:109], v[162:165], v[184:187], v[106:109]
	v_mfma_f32_16x16x32_bf16 v[110:113], v[170:173], v[184:187], v[110:113]
	v_mfma_f32_16x16x32_bf16 v[110:113], v[166:169], v[180:183], v[110:113]
	v_mfma_f32_16x16x32_bf16 v[94:97], v[166:169], v[216:219], v[94:97]
	v_mfma_f32_16x16x32_bf16 v[94:97], v[170:173], v[220:223], v[94:97]
	v_mfma_f32_16x16x32_bf16 v[90:93], v[162:165], v[220:223], v[90:93]
	v_mfma_f32_16x16x32_bf16 v[90:93], v[174:177], v[216:219], v[90:93]
	v_mfma_f32_16x16x32_bf16 v[74:77], v[174:177], v[224:227], v[74:77]
	v_mfma_f32_16x16x32_bf16 v[74:77], v[162:165], v[228:231], v[74:77]
	v_mfma_f32_16x16x32_bf16 v[78:81], v[170:173], v[228:231], v[78:81]
	v_mfma_f32_16x16x32_bf16 v[78:81], v[166:169], v[224:227], v[78:81]
	s_barrier
; #define PG8_SB(B) __builtin_amdgcn_rcpf(1.f + expneg(B))
; #define PG8_SB(B) __builtin_amdgcn_rcpf(1.f + expneg(B))
; #define PG8_STAGE(bufoff, gbase, voff) do { _Pragma("unroll") for (int _i = 0; _i < 2; ++_i) \
;         __builtin_amdgcn_global_load_lds((const unsigned*)((const char*)(gbase) + (size_t)_i * qstep + (voff)[0]), (PG8_LAS unsigned*)(lds + (bufoff) + ldsw + _i * 8192), 16, 0, 0); } while (0)
; #define PG8_LDA(dst, b, h) do { _Pragma("unroll") for (int m = 0; m < 4; ++m) _Pragma("unroll") for (int k = 0; k < 2; ++k) dst[m][k] = *(const PG8_LAS bf16x8*)(lds + PG8_SA(b, h) + aoff + m * 2048 + k * 1024); } while (0)
; #define PG8_MMA(ai, bj, At, Bt) do { __builtin_amdgcn_s_setprio(1); _Pragma("unroll") for (int m = 0; m < 4; ++m) _Pragma("unroll") for (int n = 0; n < 2; ++n) _Pragma("unroll") for (int k = 0; k < 2; ++k) \
;         acc[ai][bj][m][n] = __builtin_amdgcn_mfma_f32_16x16x32_bf16(Bt[n][k], At[m][k], acc[ai][bj][m][n], 0, 0, 0); __builtin_amdgcn_s_setprio(0); } while (0)
; #define PG8_WAIT_V89() do { if constexpr (SLIVER) PG8_WAIT_V(9); else PG8_WAIT_V(8); } while (0)
; #define PG8_LDS_S(b) do { if constexpr (SLIVER) { Sf[0] = *(const PG8_LAS bf16x8*)(lds + STAGE_BYTES + (b) * 2048 + soff0); Sf[1] = *(const PG8_LAS bf16x8*)(lds + STAGE_BYTES + (b) * 2048 + (soff0 ^ 64)); } } while (0)
; #define PG8_WAIT_L(n) asm volatile("s_waitcnt lgkmcnt(" #n ")" ::: "memory")
; #define PG8_BAR __builtin_amdgcn_s_barrier()
; #define PG8_SCHED __builtin_amdgcn_sched_barrier(0)
; template <class Epi, class Sched, bool ALIGN_EPI = false, bool SP2 = false, bool SLIVER = false>
; __device__ __forceinline__ void gemm_phase(PG8_LAS unsigned char* lds, const Gemm g, const Sched& S, const Epi& E) {
;     ...
;             PG8_LDA(At, 0, 1); PG8_LDS_S(0); PG8_STAGE(PG8_SB(0, 0), b2, voffB); PG8_STAGE(PG8_SB(0, 1), b2 + hstep, voffB); PG8_STAGE(PG8_SA(0, 0), a2, voffA);
;             PG8_WAIT_V89(); PG8_WAIT_L(0); PG8_BAR; PG8_MMA(1, 0, At, B0); PG8_MMA(1, 1, At, B1); PG8_MMA_S(); PG8_BAR; PG8_SCHED;
	s_setprio 0
	s_add_i32 s83, 0, 0x20000
	v_lshl_add_u64 v[202:203], s[78:79], 0, v[190:191]
	s_add_i32 s78, s96, s18
	v_add_u32_e32 v178, s83, v213
	v_add_u32_e32 v184, s83, v214
	s_mov_b32 m0, s78
	ds_read_b128 v[138:141], v215 offset:16384
	ds_read_b128 v[142:145], v215 offset:17408
	ds_read_b128 v[216:219], v215 offset:18432
	ds_read_b128 v[220:223], v215 offset:19456
	ds_read_b128 v[224:227], v215 offset:20480
	ds_read_b128 v[228:231], v215 offset:21504
	ds_read_b128 v[232:235], v215 offset:22528
	ds_read_b128 v[240:243], v215 offset:23552
	ds_read_b128 v[180:183], v178
	ds_read_b128 v[184:187], v184
	global_load_lds_dwordx4 v[202:203], off
	v_lshl_add_u64 v[208:209], v[202:203], 0, s[20:21]
	s_add_i32 m0, s78, 0x2000
	s_add_i32 s77, s77, s18
	global_load_lds_dwordx4 v[208:209], off
	v_lshl_add_u64 v[208:209], v[202:203], 0, s[22:23]
	s_mov_b32 m0, s77
	v_lshl_add_u64 v[210:211], s[40:41], 0, v[188:189]
	global_load_lds_dwordx4 v[208:209], off
	v_lshl_add_u64 v[208:209], v[202:203], 0, s[24:25]
	s_add_i32 m0, s77, 0x2000
	s_nop 0
	global_load_lds_dwordx4 v[208:209], off
	s_mov_b32 m0, s85
	v_lshl_add_u64 v[208:209], v[210:211], 0, s[20:21]
	global_load_lds_dwordx4 v[210:211], off
	s_mov_b32 m0, s19
	s_nop 0
	global_load_lds_dwordx4 v[208:209], off
	s_waitcnt vmcnt(9)
	s_waitcnt lgkmcnt(0)
	s_setprio 1
	s_barrier
	v_mfma_f32_16x16x32_bf16 v[70:73], v[146:149], v[138:141], v[70:73]
	v_mfma_f32_16x16x32_bf16 v[70:73], v[150:153], v[142:145], v[70:73]
	v_mfma_f32_16x16x32_bf16 v[66:69], v[158:161], v[142:145], v[66:69]
	v_mfma_f32_16x16x32_bf16 v[66:69], v[154:157], v[138:141], v[66:69]
	v_mfma_f32_16x16x32_bf16 v[50:53], v[154:157], v[216:219], v[50:53]
	v_mfma_f32_16x16x32_bf16 v[50:53], v[158:161], v[220:223], v[50:53]
	v_mfma_f32_16x16x32_bf16 v[54:57], v[150:153], v[220:223], v[54:57]
	v_mfma_f32_16x16x32_bf16 v[54:57], v[146:149], v[216:219], v[54:57]
	v_mfma_f32_16x16x32_bf16 v[38:41], v[146:149], v[224:227], v[38:41]
	v_mfma_f32_16x16x32_bf16 v[38:41], v[150:153], v[228:231], v[38:41]
	v_mfma_f32_16x16x32_bf16 v[34:37], v[158:161], v[228:231], v[34:37]
	v_mfma_f32_16x16x32_bf16 v[34:37], v[154:157], v[224:227], v[34:37]
	v_mfma_f32_16x16x32_bf16 v[18:21], v[154:157], v[232:235], v[18:21]
	v_mfma_f32_16x16x32_bf16 v[18:21], v[158:161], v[240:243], v[18:21]
	v_mfma_f32_16x16x32_bf16 v[22:25], v[150:153], v[240:243], v[22:25]
	v_mfma_f32_16x16x32_bf16 v[22:25], v[146:149], v[232:235], v[22:25]
	s_setprio 0
	s_setprio 1
	v_mfma_f32_16x16x32_bf16 v[62:65], v[166:169], v[138:141], v[62:65]
	v_mfma_f32_16x16x32_bf16 v[62:65], v[170:173], v[142:145], v[62:65]
	v_mfma_f32_16x16x32_bf16 v[58:61], v[162:165], v[142:145], v[58:61]
	v_mfma_f32_16x16x32_bf16 v[58:61], v[174:177], v[138:141], v[58:61]
	v_mfma_f32_16x16x32_bf16 v[42:45], v[174:177], v[216:219], v[42:45]
	v_mfma_f32_16x16x32_bf16 v[42:45], v[162:165], v[220:223], v[42:45]
	v_mfma_f32_16x16x32_bf16 v[46:49], v[170:173], v[220:223], v[46:49]
	v_mfma_f32_16x16x32_bf16 v[46:49], v[166:169], v[216:219], v[46:49]
	v_mfma_f32_16x16x32_bf16 v[30:33], v[166:169], v[224:227], v[30:33]
	v_mfma_f32_16x16x32_bf16 v[30:33], v[170:173], v[228:231], v[30:33]
	v_mfma_f32_16x16x32_bf16 v[26:29], v[162:165], v[228:231], v[26:29]
	v_mfma_f32_16x16x32_bf16 v[26:29], v[174:177], v[224:227], v[26:29]
	v_mfma_f32_16x16x32_bf16 v[10:13], v[174:177], v[232:235], v[10:13]
	v_mfma_f32_16x16x32_bf16 v[10:13], v[162:165], v[240:243], v[10:13]
	v_mfma_f32_16x16x32_bf16 v[14:17], v[170:173], v[240:243], v[14:17]
	v_mfma_f32_16x16x32_bf16 v[14:17], v[166:169], v[232:235], v[14:17]
	s_setprio 0
	s_setprio 1
	s_and_b64 vcc, exec, s[52:53]
	s_cbranch_vccz .Lslv_b1
	v_mfma_f32_16x16x32_bf16 v[138:141], v[166:169], v[180:183], v[6:9]
	v_mfma_f32_16x16x32_bf16 v[142:145], v[174:177], v[180:183], v[2:5]
	v_mfma_f32_16x16x32_bf16 v[138:141], v[170:173], v[184:187], v[138:141]
	v_mfma_f32_16x16x32_bf16 v[142:145], v[162:165], v[184:187], v[142:145]
	s_branch .LBB0_602

; #define PG8_STAGE(bufoff, gbase, voff) do { _Pragma("unroll") for (int _i = 0; _i < 2; ++_i) \
;         __builtin_amdgcn_global_load_lds((const unsigned*)((const char*)(gbase) + (size_t)_i * qstep + (voff)[0]), (PG8_LAS unsigned*)(lds + (bufoff) + ldsw + _i * 8192), 16, 0, 0); } while (0)
; #define PG8_LDA(dst, b, h) do { _Pragma("unroll") for (int m = 0; m < 4; ++m) _Pragma("unroll") for (int k = 0; k < 2; ++k) dst[m][k] = *(const PG8_LAS bf16x8*)(lds + PG8_SA(b, h) + aoff + m * 2048 + k * 1024); } while (0)
; #define PG8_LDB(dst, b, h) do { _Pragma("unroll") for (int n = 0; n < 2; ++n) _Pragma("unroll") for (int k = 0; k < 2; ++k) dst[n][k] = *(const PG8_LAS bf16x8*)(lds + PG8_SB(b, h) + boff + n * 2048 + k * 1024); } while (0)
; #define PG8_MMA(ai, bj, At, Bt) do { __builtin_amdgcn_s_setprio(1); _Pragma("unroll") for (int m = 0; m < 4; ++m) _Pragma("unroll") for (int n = 0; n < 2; ++n) _Pragma("unroll") for (int k = 0; k < 2; ++k) \
;         acc[ai][bj][m][n] = __builtin_amdgcn_mfma_f32_16x16x32_bf16(Bt[n][k], At[m][k], acc[ai][bj][m][n], 0, 0, 0); __builtin_amdgcn_s_setprio(0); } while (0)
; #define PG8_WAIT_V89() do { if constexpr (SLIVER) PG8_WAIT_V(9); else PG8_WAIT_V(8); } while (0)
; #define PG8_STAGE_S(b, gbase) do { if constexpr (SLIVER) __builtin_amdgcn_global_load_lds((const unsigned*)((const char*)(gbase) + voffS), (PG8_LAS unsigned*)(lds + STAGE_BYTES + (b) * 2048 + wid * 256), 4, 0, 0); } while (0)
; #define PG8_WAIT_L(n) asm volatile("s_waitcnt lgkmcnt(" #n ")" ::: "memory")
; #define PG8_BAR __builtin_amdgcn_s_barrier()
; #define PG8_SCHED __builtin_amdgcn_sched_barrier(0)
; template <class Epi, class Sched, bool ALIGN_EPI = false, bool SP2 = false, bool SLIVER = false>
; __device__ __forceinline__ void gemm_phase(PG8_LAS unsigned char* lds, const Gemm g, const Sched& S, const Epi& E) {
;     ...
;             PG8_LDB(B0, 1, 0); PG8_LDB(B1, 1, 1); PG8_SCHED; PG8_LDA(At, 1, 0); PG8_STAGE(PG8_SA(0, 1), a2 + hstep, voffA); PG8_STAGE_S(0, s2);
;             PG8_WAIT_V89(); PG8_WAIT_L(0); PG8_BAR; PG8_MMA(0, 0, At, B0); PG8_MMA(0, 1, At, B1); PG8_BAR; PG8_SCHED;
.LBB0_602:
	s_barrier
	s_setprio 0
	s_add_u32 s77, s94, s62
	s_addc_u32 s78, s95, s63
	s_add_u32 s77, s77, 0x100
	s_addc_u32 s83, s78, 0
	s_and_b64 s[78:79], s[80:81], exec
	s_cselect_b32 s79, s66, s83
	s_cselect_b32 s78, s67, s77
	s_add_i32 s77, 0, 0x18000
	v_add_u32_e32 v2, s77, v212
	s_add_i32 s80, 0, 0x1c000
	ds_read_b128 v[146:149], v2
	ds_read_b128 v[150:153], v2 offset:1024
	ds_read_b128 v[154:157], v2 offset:2048
	ds_read_b128 v[158:161], v2 offset:3072
	v_add_u32_e32 v2, s80, v212
	ds_read_b128 v[166:169], v2
	ds_read_b128 v[170:173], v2 offset:1024
	ds_read_b128 v[174:177], v2 offset:2048
	ds_read_b128 v[162:165], v2 offset:3072
	s_mov_b32 m0, s49
	v_lshl_add_u64 v[208:209], v[210:211], 0, s[22:23]
	ds_read_b128 v[2:5], v215 offset:32768
	ds_read_b128 v[6:9], v215 offset:33792
	ds_read_b128 v[180:183], v215 offset:34816
	ds_read_b128 v[184:187], v215 offset:35840
	ds_read_b128 v[216:219], v215 offset:36864
	ds_read_b128 v[220:223], v215 offset:37888
	ds_read_b128 v[224:227], v215 offset:38912
	ds_read_b128 v[228:231], v215 offset:39936
	global_load_lds_dwordx4 v[208:209], off
	v_lshl_add_u64 v[208:209], v[210:211], 0, s[24:25]
	s_mov_b32 m0, s50
	s_nop 0
	global_load_lds_dwordx4 v[208:209], off
	v_lshl_add_u64 v[208:209], s[78:79], 0, v[192:193]
	s_mov_b32 m0, s51
	s_nop 0
	global_load_lds_dword v[208:209], off
	s_waitcnt vmcnt(9)
	s_waitcnt lgkmcnt(0)
	s_setprio 1
	s_barrier
	v_mfma_f32_16x16x32_bf16 v[134:137], v[146:149], v[2:5], v[134:137]
	v_mfma_f32_16x16x32_bf16 v[134:137], v[150:153], v[6:9], v[134:137]
	v_mfma_f32_16x16x32_bf16 v[130:133], v[158:161], v[6:9], v[130:133]
	v_mfma_f32_16x16x32_bf16 v[130:133], v[154:157], v[2:5], v[130:133]
	v_mfma_f32_16x16x32_bf16 v[114:117], v[154:157], v[180:183], v[114:117]
	v_mfma_f32_16x16x32_bf16 v[114:117], v[158:161], v[184:187], v[114:117]
	v_mfma_f32_16x16x32_bf16 v[118:121], v[150:153], v[184:187], v[118:121]
	v_mfma_f32_16x16x32_bf16 v[118:121], v[146:149], v[180:183], v[118:121]
	v_mfma_f32_16x16x32_bf16 v[102:105], v[146:149], v[216:219], v[102:105]
	v_mfma_f32_16x16x32_bf16 v[102:105], v[150:153], v[220:223], v[102:105]
	v_mfma_f32_16x16x32_bf16 v[98:101], v[158:161], v[220:223], v[98:101]
	v_mfma_f32_16x16x32_bf16 v[98:101], v[154:157], v[216:219], v[98:101]
	v_mfma_f32_16x16x32_bf16 v[82:85], v[154:157], v[224:227], v[82:85]
	v_mfma_f32_16x16x32_bf16 v[82:85], v[158:161], v[228:231], v[82:85]
	v_mfma_f32_16x16x32_bf16 v[86:89], v[150:153], v[228:231], v[86:89]
	v_mfma_f32_16x16x32_bf16 v[86:89], v[146:149], v[224:227], v[86:89]
	s_setprio 0
	s_setprio 1
	v_mfma_f32_16x16x32_bf16 v[126:129], v[166:169], v[2:5], v[126:129]
	v_mfma_f32_16x16x32_bf16 v[126:129], v[170:173], v[6:9], v[126:129]
	v_mfma_f32_16x16x32_bf16 v[2:5], v[174:177], v[2:5], v[122:125]
	v_mfma_f32_16x16x32_bf16 v[122:125], v[162:165], v[6:9], v[2:5]
	v_mfma_f32_16x16x32_bf16 v[2:5], v[166:169], v[180:183], v[110:113]
	v_mfma_f32_16x16x32_bf16 v[110:113], v[170:173], v[184:187], v[2:5]
	v_mfma_f32_16x16x32_bf16 v[2:5], v[174:177], v[180:183], v[106:109]
	v_mfma_f32_16x16x32_bf16 v[106:109], v[162:165], v[184:187], v[2:5]
	v_mfma_f32_16x16x32_bf16 v[2:5], v[166:169], v[216:219], v[94:97]
	v_mfma_f32_16x16x32_bf16 v[94:97], v[170:173], v[220:223], v[2:5]
	v_mfma_f32_16x16x32_bf16 v[2:5], v[174:177], v[216:219], v[90:93]
	v_mfma_f32_16x16x32_bf16 v[90:93], v[162:165], v[220:223], v[2:5]
	v_mfma_f32_16x16x32_bf16 v[2:5], v[166:169], v[224:227], v[78:81]
	v_mfma_f32_16x16x32_bf16 v[78:81], v[170:173], v[228:231], v[2:5]
	v_mfma_f32_16x16x32_bf16 v[2:5], v[174:177], v[224:227], v[74:77]
	v_mfma_f32_16x16x32_bf16 v[74:77], v[162:165], v[228:231], v[2:5]
	s_barrier
; #define PG8_SB(B) __builtin_amdgcn_rcpf(1.f + expneg(B))
; #define PG8_SB(B) __builtin_amdgcn_rcpf(1.f + expneg(B))
; #define PG8_STAGE(bufoff, gbase, voff) do { _Pragma("unroll") for (int _i = 0; _i < 2; ++_i) \
;         __builtin_amdgcn_global_load_lds((const unsigned*)((const char*)(gbase) + (size_t)_i * qstep + (voff)[0]), (PG8_LAS unsigned*)(lds + (bufoff) + ldsw + _i * 8192), 16, 0, 0); } while (0)
; #define PG8_LDA(dst, b, h) do { _Pragma("unroll") for (int m = 0; m < 4; ++m) _Pragma("unroll") for (int k = 0; k < 2; ++k) dst[m][k] = *(const PG8_LAS bf16x8*)(lds + PG8_SA(b, h) + aoff + m * 2048 + k * 1024); } while (0)
; #define PG8_MMA(ai, bj, At, Bt) do { __builtin_amdgcn_s_setprio(1); _Pragma("unroll") for (int m = 0; m < 4; ++m) _Pragma("unroll") for (int n = 0; n < 2; ++n) _Pragma("unroll") for (int k = 0; k < 2; ++k) \
;         acc[ai][bj][m][n] = __builtin_amdgcn_mfma_f32_16x16x32_bf16(Bt[n][k], At[m][k], acc[ai][bj][m][n], 0, 0, 0); __builtin_amdgcn_s_setprio(0); } while (0)
; #define PG8_WAIT_V89() do { if constexpr (SLIVER) PG8_WAIT_V(9); else PG8_WAIT_V(8); } while (0)
; #define PG8_LDS_S(b) do { if constexpr (SLIVER) { Sf[0] = *(const PG8_LAS bf16x8*)(lds + STAGE_BYTES + (b) * 2048 + soff0); Sf[1] = *(const PG8_LAS bf16x8*)(lds + STAGE_BYTES + (b) * 2048 + (soff0 ^ 64)); } } while (0)
; #define PG8_WAIT_L(n) asm volatile("s_waitcnt lgkmcnt(" #n ")" ::: "memory")
; #define PG8_BAR __builtin_amdgcn_s_barrier()
; #define PG8_SCHED __builtin_amdgcn_sched_barrier(0)
; template <class Epi, class Sched, bool ALIGN_EPI = false, bool SP2 = false, bool SLIVER = false>
; __device__ __forceinline__ void gemm_phase(PG8_LAS unsigned char* lds, const Gemm g, const Sched& S, const Epi& E) {
;     ...
;             PG8_LDA(At, 1, 1); PG8_LDS_S(1); PG8_STAGE(PG8_SB(1, 0), b3, voffB); PG8_STAGE(PG8_SB(1, 1), b3 + hstep, voffB); PG8_STAGE(PG8_SA(1, 0), a3, voffA);
;             PG8_WAIT_V89(); PG8_WAIT_L(0); PG8_BAR; PG8_MMA(1, 0, At, B0); PG8_MMA(1, 1, At, B1); PG8_MMA_S(); PG8_BAR; PG8_SCHED;
	s_setprio 0
	s_add_i32 s78, 0, 0x20800
	s_add_i32 s77, s77, s18
	v_add_u32_e32 v178, s78, v213
	v_add_u32_e32 v184, s78, v214
	v_lshl_add_u64 v[208:209], v[202:203], 0, s[26:27]
	s_mov_b32 m0, s77
	ds_read_b128 v[2:5], v215 offset:49152
	ds_read_b128 v[6:9], v215 offset:50176
	ds_read_b128 v[216:219], v215 offset:51200
	ds_read_b128 v[220:223], v215 offset:52224
	ds_read_b128 v[224:227], v215 offset:53248
	ds_read_b128 v[228:231], v215 offset:54272
	ds_read_b128 v[232:235], v215 offset:55296
	ds_read_b128 v[240:243], v215 offset:56320
	ds_read_b128 v[180:183], v178
	ds_read_b128 v[184:187], v184
	global_load_lds_dwordx4 v[208:209], off
	v_lshl_add_u64 v[208:209], v[202:203], 0, s[28:29]
	s_add_i32 m0, s77, 0x2000
	s_add_i32 s77, s80, s18
	global_load_lds_dwordx4 v[208:209], off
	v_lshl_add_u64 v[208:209], v[202:203], 0, s[30:31]
	s_mov_b32 m0, s77
	v_lshl_add_u64 v[202:203], v[202:203], 0, s[34:35]
	global_load_lds_dwordx4 v[208:209], off
	s_add_i32 m0, s77, 0x2000
	s_nop 0
	global_load_lds_dwordx4 v[202:203], off
	v_lshl_add_u64 v[202:203], v[210:211], 0, s[26:27]
	s_mov_b32 m0, s10
	s_nop 0
	global_load_lds_dwordx4 v[202:203], off
	v_lshl_add_u64 v[202:203], v[210:211], 0, s[28:29]
	s_mov_b32 m0, s2
	s_nop 0
	global_load_lds_dwordx4 v[202:203], off
	s_waitcnt vmcnt(9)
	s_waitcnt lgkmcnt(0)
	s_setprio 1
	s_barrier
	v_mfma_f32_16x16x32_bf16 v[70:73], v[146:149], v[2:5], v[70:73]
	v_mfma_f32_16x16x32_bf16 v[70:73], v[150:153], v[6:9], v[70:73]
	v_mfma_f32_16x16x32_bf16 v[66:69], v[158:161], v[6:9], v[66:69]
	v_mfma_f32_16x16x32_bf16 v[66:69], v[154:157], v[2:5], v[66:69]
	v_mfma_f32_16x16x32_bf16 v[50:53], v[154:157], v[216:219], v[50:53]
	v_mfma_f32_16x16x32_bf16 v[50:53], v[158:161], v[220:223], v[50:53]
	v_mfma_f32_16x16x32_bf16 v[54:57], v[150:153], v[220:223], v[54:57]
	v_mfma_f32_16x16x32_bf16 v[54:57], v[146:149], v[216:219], v[54:57]
	v_mfma_f32_16x16x32_bf16 v[38:41], v[146:149], v[224:227], v[38:41]
	v_mfma_f32_16x16x32_bf16 v[38:41], v[150:153], v[228:231], v[38:41]
	v_mfma_f32_16x16x32_bf16 v[34:37], v[158:161], v[228:231], v[34:37]
	v_mfma_f32_16x16x32_bf16 v[34:37], v[154:157], v[224:227], v[34:37]
	v_mfma_f32_16x16x32_bf16 v[18:21], v[154:157], v[232:235], v[18:21]
	v_mfma_f32_16x16x32_bf16 v[18:21], v[158:161], v[240:243], v[18:21]
	v_mfma_f32_16x16x32_bf16 v[22:25], v[150:153], v[240:243], v[22:25]
	v_mfma_f32_16x16x32_bf16 v[22:25], v[146:149], v[232:235], v[22:25]
	s_setprio 0
	s_setprio 1
	v_mfma_f32_16x16x32_bf16 v[62:65], v[166:169], v[2:5], v[62:65]
	v_mfma_f32_16x16x32_bf16 v[62:65], v[170:173], v[6:9], v[62:65]
	v_mfma_f32_16x16x32_bf16 v[2:5], v[174:177], v[2:5], v[58:61]
	v_mfma_f32_16x16x32_bf16 v[58:61], v[162:165], v[6:9], v[2:5]
	v_mfma_f32_16x16x32_bf16 v[2:5], v[166:169], v[216:219], v[46:49]
	v_mfma_f32_16x16x32_bf16 v[46:49], v[170:173], v[220:223], v[2:5]
	v_mfma_f32_16x16x32_bf16 v[2:5], v[174:177], v[216:219], v[42:45]
	v_mfma_f32_16x16x32_bf16 v[42:45], v[162:165], v[220:223], v[2:5]
	v_mfma_f32_16x16x32_bf16 v[2:5], v[166:169], v[224:227], v[30:33]
	v_mfma_f32_16x16x32_bf16 v[30:33], v[170:173], v[228:231], v[2:5]
	v_mfma_f32_16x16x32_bf16 v[2:5], v[174:177], v[224:227], v[26:29]
	v_mfma_f32_16x16x32_bf16 v[26:29], v[162:165], v[228:231], v[2:5]
	v_mfma_f32_16x16x32_bf16 v[2:5], v[166:169], v[232:235], v[14:17]
	v_mfma_f32_16x16x32_bf16 v[14:17], v[170:173], v[240:243], v[2:5]
	v_mfma_f32_16x16x32_bf16 v[2:5], v[174:177], v[232:235], v[10:13]
	v_mfma_f32_16x16x32_bf16 v[10:13], v[162:165], v[240:243], v[2:5]
	s_setprio 0
	s_setprio 1
	s_and_b64 vcc, exec, s[52:53]
	s_cbranch_vccz .Lslv_c1
	v_mfma_f32_16x16x32_bf16 v[2:5], v[166:169], v[180:183], v[138:141]
	v_mfma_f32_16x16x32_bf16 v[6:9], v[170:173], v[184:187], v[2:5]
	v_mfma_f32_16x16x32_bf16 v[2:5], v[174:177], v[180:183], v[142:145]
	v_mfma_f32_16x16x32_bf16 v[2:5], v[162:165], v[184:187], v[2:5]
	s_branch .LBB0_597

; #define PG8_STAGE(bufoff, gbase, voff) do { _Pragma("unroll") for (int _i = 0; _i < 2; ++_i) \
;         __builtin_amdgcn_global_load_lds((const unsigned*)((const char*)(gbase) + (size_t)_i * qstep + (voff)[0]), (PG8_LAS unsigned*)(lds + (bufoff) + ldsw + _i * 8192), 16, 0, 0); } while (0)
; #define PG8_LDA(dst, b, h) do { _Pragma("unroll") for (int m = 0; m < 4; ++m) _Pragma("unroll") for (int k = 0; k < 2; ++k) dst[m][k] = *(const PG8_LAS bf16x8*)(lds + PG8_SA(b, h) + aoff + m * 2048 + k * 1024); } while (0)
; #define PG8_LDB(dst, b, h) do { _Pragma("unroll") for (int n = 0; n < 2; ++n) _Pragma("unroll") for (int k = 0; k < 2; ++k) dst[n][k] = *(const PG8_LAS bf16x8*)(lds + PG8_SB(b, h) + boff + n * 2048 + k * 1024); } while (0)
; #define PG8_WAIT_V89() do { if constexpr (SLIVER) PG8_WAIT_V(9); else PG8_WAIT_V(8); } while (0)
; #define PG8_WAIT_L(n) asm volatile("s_waitcnt lgkmcnt(" #n ")" ::: "memory")
; template <class Epi, class Sched, bool ALIGN_EPI = false, bool SP2 = false, bool SLIVER = false>
; __device__ __forceinline__ void gemm_phase(PG8_LAS unsigned char* lds, const Gemm g, const Sched& S, const Epi& E) {
;     ...
;         const bool has_next = S.next(ui + 1, nxt);
;         const char* nA = has_next ? (const char*)g.A + (size_t)nxt.pm * tstep + Epi::k0(nxt.seg) * 2 : cA; const char* nB = has_next ? (const char*)g.Bt + (size_t)nxt.pn * tstep + Epi::k0(nxt.seg) * 2 : cB;
;         const char* nS = has_next ? (const char*)g.A + (size_t)S.srow0 * K * 2 + (size_t)nxt.pm * sstep + Epi::k0(nxt.seg) * 2 : cS;
;         for (int t = 0; t < nt; t += 2) {
;             const bool last = (t == nt - 2);
;             const char* a1 = cA + (size_t)(t + 1) * kstep;
;             const char* a2 = last ? nA : cA + (size_t)(t + 2) * kstep; const char* b2 = last ? nB : cB + (size_t)(t + 2) * kstep;
;             const char* a3 = a2 + kstep; const char* b3 = b2 + kstep;
;             const char* s1 = cS + (size_t)(t + 1) * kstep; const char* s2 = last ? nS : cS + (size_t)(t + 2) * kstep;
;             if (last && has_next) S.a_ready(nxt);
;             if constexpr (SP2) {
;             PG8_LDB(B0, 0, 0); PG8_LDB(B1, 0, 1); PG8_SCHED; PG8_LDA(At, 0, 0); PG8_STAGE(PG8_SA(1, 1), a1 + hstep, voffA); PG8_STAGE_S(1, s1);
;             PG8_WAIT_V89(); PG8_WAIT_L(0); PG8_BAR; PG8_MMA(0, 0, At, B0); PG8_MMA(0, 1, At, B1); PG8_BAR; PG8_SCHED;
.LBB0_811:
	s_add_u32 s13, s90, s62
	s_addc_u32 s40, s91, s63
	s_add_u32 s13, s13, 0x100
	s_addc_u32 s66, s40, 0
	s_add_u32 s68, s2, s62
	s_addc_u32 s67, s3, s63
	s_add_i32 s69, 0, 0x10000
	s_cmpk_eq_i32 s62, 0x2b00
	s_cselect_b64 s[80:81], -1, 0
	s_and_b64 s[40:41], s[80:81], exec
	s_cselect_b32 s41, s85, s66
	s_cselect_b32 s40, s84, s13
	v_add_u32_e32 v66, s69, v220
	s_cselect_b32 s67, s87, s67
	s_cselect_b32 s66, s86, s68
	s_add_i32 s13, 0, 0x14000
	ds_read_b128 v[154:157], v66
	ds_read_b128 v[158:161], v66 offset:1024
	ds_read_b128 v[162:165], v66 offset:2048
	ds_read_b128 v[174:177], v66 offset:3072
	v_add_u32_e32 v66, s13, v220
	ds_read_b128 v[184:187], v66
	ds_read_b128 v[188:191], v66 offset:1024
	ds_read_b128 v[192:195], v66 offset:2048
	ds_read_b128 v[180:183], v66 offset:3072
	v_lshl_add_u64 v[146:147], v[214:215], 0, s[62:63]
	v_lshl_add_u64 v[148:149], v[146:147], 0, s[8:9]
	s_add_i32 m0, s19, 0xc000
	s_mov_b64 s[94:95], 0x210080
	ds_read_b128 v[66:69], v223
	ds_read_b128 v[70:73], v223 offset:1024
	ds_read_b128 v[74:77], v223 offset:2048
	ds_read_b128 v[78:81], v223 offset:3072
	ds_read_b128 v[216:219], v223 offset:4096
	ds_read_b128 v[224:227], v223 offset:5120
	ds_read_b128 v[228:231], v223 offset:6144
	ds_read_b128 v[232:235], v223 offset:7168
	global_load_lds_dwordx4 v[148:149], off
	v_lshl_add_u64 v[146:147], v[146:147], 0, s[94:95]
	s_add_i32 m0, s19, 0xe000
	s_nop 0
	global_load_lds_dwordx4 v[146:147], off
	v_lshl_add_u64 v[146:147], v[212:213], 0, s[62:63]
	s_add_i32 m0, s96, 0x20800
	s_nop 0
	global_load_lds_dword v[146:147], off
	s_waitcnt vmcnt(9)
	s_waitcnt lgkmcnt(0)
	s_setprio 1
	s_barrier
	v_mfma_f32_16x16x32_bf16 v[146:149], v[154:157], v[66:69], v[170:173]
	v_mfma_f32_16x16x32_bf16 v[146:149], v[158:161], v[70:73], v[146:149]
	v_mfma_f32_16x16x32_bf16 v[150:153], v[162:165], v[66:69], v[166:169]
	v_mfma_f32_16x16x32_bf16 v[150:153], v[174:177], v[70:73], v[150:153]
	v_mfma_f32_16x16x32_bf16 v[134:137], v[154:157], v[74:77], v[134:137]
	v_mfma_f32_16x16x32_bf16 v[134:137], v[158:161], v[78:81], v[134:137]
	v_mfma_f32_16x16x32_bf16 v[130:133], v[162:165], v[74:77], v[130:133]
	v_mfma_f32_16x16x32_bf16 v[130:133], v[174:177], v[78:81], v[130:133]
	v_mfma_f32_16x16x32_bf16 v[118:121], v[154:157], v[216:219], v[118:121]
	v_mfma_f32_16x16x32_bf16 v[118:121], v[158:161], v[224:227], v[118:121]
	v_mfma_f32_16x16x32_bf16 v[114:117], v[162:165], v[216:219], v[114:117]
	v_mfma_f32_16x16x32_bf16 v[114:117], v[174:177], v[224:227], v[114:117]
	v_mfma_f32_16x16x32_bf16 v[102:105], v[154:157], v[228:231], v[102:105]
	v_mfma_f32_16x16x32_bf16 v[102:105], v[158:161], v[232:235], v[102:105]
	v_mfma_f32_16x16x32_bf16 v[98:101], v[162:165], v[228:231], v[98:101]
	v_mfma_f32_16x16x32_bf16 v[98:101], v[174:177], v[232:235], v[98:101]
	s_setprio 0
	s_setprio 1
	v_mfma_f32_16x16x32_bf16 v[142:145], v[184:187], v[66:69], v[142:145]
	v_mfma_f32_16x16x32_bf16 v[142:145], v[188:191], v[70:73], v[142:145]
	v_mfma_f32_16x16x32_bf16 v[66:69], v[192:195], v[66:69], v[138:141]
	v_mfma_f32_16x16x32_bf16 v[138:141], v[180:183], v[70:73], v[66:69]
	v_mfma_f32_16x16x32_bf16 v[66:69], v[184:187], v[74:77], v[126:129]
	v_mfma_f32_16x16x32_bf16 v[126:129], v[188:191], v[78:81], v[66:69]
	v_mfma_f32_16x16x32_bf16 v[66:69], v[192:195], v[74:77], v[122:125]
	v_mfma_f32_16x16x32_bf16 v[122:125], v[180:183], v[78:81], v[66:69]
	v_mfma_f32_16x16x32_bf16 v[66:69], v[184:187], v[216:219], v[110:113]
	v_mfma_f32_16x16x32_bf16 v[110:113], v[188:191], v[224:227], v[66:69]
	v_mfma_f32_16x16x32_bf16 v[66:69], v[192:195], v[216:219], v[106:109]
	v_mfma_f32_16x16x32_bf16 v[106:109], v[180:183], v[224:227], v[66:69]
	v_mfma_f32_16x16x32_bf16 v[66:69], v[184:187], v[228:231], v[94:97]
	v_mfma_f32_16x16x32_bf16 v[94:97], v[188:191], v[232:235], v[66:69]
	v_mfma_f32_16x16x32_bf16 v[66:69], v[192:195], v[228:231], v[90:93]
	v_mfma_f32_16x16x32_bf16 v[90:93], v[180:183], v[232:235], v[66:69]
	s_barrier
; #define PG8_SB(B) __builtin_amdgcn_rcpf(1.f + expneg(B))
; #define PG8_SB(B) __builtin_amdgcn_rcpf(1.f + expneg(B))
; #define PG8_STAGE(bufoff, gbase, voff) do { _Pragma("unroll") for (int _i = 0; _i < 2; ++_i) \
;         __builtin_amdgcn_global_load_lds((const unsigned*)((const char*)(gbase) + (size_t)_i * qstep + (voff)[0]), (PG8_LAS unsigned*)(lds + (bufoff) + ldsw + _i * 8192), 16, 0, 0); } while (0)
; #define PG8_LDA(dst, b, h) do { _Pragma("unroll") for (int m = 0; m < 4; ++m) _Pragma("unroll") for (int k = 0; k < 2; ++k) dst[m][k] = *(const PG8_LAS bf16x8*)(lds + PG8_SA(b, h) + aoff + m * 2048 + k * 1024); } while (0)
; #define PG8_MMA(ai, bj, At, Bt) do { __builtin_amdgcn_s_setprio(1); _Pragma("unroll") for (int m = 0; m < 4; ++m) _Pragma("unroll") for (int n = 0; n < 2; ++n) _Pragma("unroll") for (int k = 0; k < 2; ++k) \
;         acc[ai][bj][m][n] = __builtin_amdgcn_mfma_f32_16x16x32_bf16(Bt[n][k], At[m][k], acc[ai][bj][m][n], 0, 0, 0); __builtin_amdgcn_s_setprio(0); } while (0)
; #define PG8_WAIT_V89() do { if constexpr (SLIVER) PG8_WAIT_V(9); else PG8_WAIT_V(8); } while (0)
; #define PG8_LDS_S(b) do { if constexpr (SLIVER) { Sf[0] = *(const PG8_LAS bf16x8*)(lds + STAGE_BYTES + (b) * 2048 + soff0); Sf[1] = *(const PG8_LAS bf16x8*)(lds + STAGE_BYTES + (b) * 2048 + (soff0 ^ 64)); } } while (0)
; #define PG8_WAIT_L(n) asm volatile("s_waitcnt lgkmcnt(" #n ")" ::: "memory")
; #define PG8_BAR __builtin_amdgcn_s_barrier()
; #define PG8_SCHED __builtin_amdgcn_sched_barrier(0)
; template <class Epi, class Sched, bool ALIGN_EPI = false, bool SP2 = false, bool SLIVER = false>
; __device__ __forceinline__ void gemm_phase(PG8_LAS unsigned char* lds, const Gemm g, const Sched& S, const Epi& E) {
;     ...
;             PG8_LDA(At, 0, 1); PG8_LDS_S(0); PG8_STAGE(PG8_SB(0, 0), b2, voffB); PG8_STAGE(PG8_SB(0, 1), b2 + hstep, voffB); PG8_STAGE(PG8_SA(0, 0), a2, voffA);
;             PG8_WAIT_V89(); PG8_WAIT_L(0); PG8_BAR; PG8_MMA(1, 0, At, B0); PG8_MMA(1, 1, At, B1); PG8_MMA_S(); PG8_BAR; PG8_SCHED;
	s_setprio 0
	s_add_i32 s68, 0, 0x20000
	v_lshl_add_u64 v[216:217], s[66:67], 0, v[198:199]
	s_add_i32 s66, s69, s18
	v_add_u32_e32 v74, s68, v221
	v_add_u32_e32 v75, s68, v222
	s_mov_b32 m0, s66
	ds_read_b128 v[66:69], v223 offset:16384
	ds_read_b128 v[70:73], v223 offset:17408
	ds_read_b128 v[224:227], v223 offset:18432
	ds_read_b128 v[228:231], v223 offset:19456
	ds_read_b128 v[232:235], v223 offset:20480
	ds_read_b128 v[240:243], v223 offset:21504
	ds_read_b128 v[244:247], v223 offset:22528
	ds_read_b128 v[248:251], v223 offset:23552
	ds_read_b128 v[166:169], v74
	ds_read_b128 v[170:173], v75
	global_load_lds_dwordx4 v[216:217], off
	v_lshl_add_u64 v[74:75], v[216:217], 0, s[64:65]
	s_add_i32 m0, s66, 0x2000
	s_add_i32 s13, s13, s18
	global_load_lds_dwordx4 v[74:75], off
	v_lshl_add_u64 v[74:75], v[216:217], 0, s[0:1]
	s_mov_b32 m0, s13
	v_lshl_add_u64 v[218:219], s[40:41], 0, v[196:197]
	global_load_lds_dwordx4 v[74:75], off
	v_lshl_add_u64 v[74:75], v[216:217], 0, s[74:75]
	s_add_i32 m0, s13, 0x2000
	s_nop 0
	global_load_lds_dwordx4 v[74:75], off
	s_mov_b32 m0, s19
	v_lshl_add_u64 v[74:75], v[218:219], 0, s[64:65]
	global_load_lds_dwordx4 v[218:219], off
	s_mov_b32 m0, s52
	s_nop 0
	global_load_lds_dwordx4 v[74:75], off
	s_waitcnt vmcnt(9)
	s_waitcnt lgkmcnt(0)
	s_setprio 1
	s_barrier
	v_mfma_f32_16x16x32_bf16 v[74:77], v[154:157], v[66:69], v[86:89]
	v_mfma_f32_16x16x32_bf16 v[74:77], v[158:161], v[70:73], v[74:77]
	v_mfma_f32_16x16x32_bf16 v[78:81], v[162:165], v[66:69], v[82:85]
	v_mfma_f32_16x16x32_bf16 v[78:81], v[174:177], v[70:73], v[78:81]
	v_mfma_f32_16x16x32_bf16 v[54:57], v[154:157], v[224:227], v[54:57]
	v_mfma_f32_16x16x32_bf16 v[54:57], v[158:161], v[228:231], v[54:57]
	v_mfma_f32_16x16x32_bf16 v[50:53], v[162:165], v[224:227], v[50:53]
	v_mfma_f32_16x16x32_bf16 v[50:53], v[174:177], v[228:231], v[50:53]
	v_mfma_f32_16x16x32_bf16 v[38:41], v[154:157], v[232:235], v[38:41]
	v_mfma_f32_16x16x32_bf16 v[38:41], v[158:161], v[240:243], v[38:41]
	v_mfma_f32_16x16x32_bf16 v[34:37], v[162:165], v[232:235], v[34:37]
	v_mfma_f32_16x16x32_bf16 v[34:37], v[174:177], v[240:243], v[34:37]
	v_mfma_f32_16x16x32_bf16 v[22:25], v[154:157], v[244:247], v[22:25]
	v_mfma_f32_16x16x32_bf16 v[22:25], v[158:161], v[248:251], v[22:25]
	v_mfma_f32_16x16x32_bf16 v[18:21], v[162:165], v[244:247], v[18:21]
	v_mfma_f32_16x16x32_bf16 v[18:21], v[174:177], v[248:251], v[18:21]
	s_setprio 0
	s_setprio 1
	v_mfma_f32_16x16x32_bf16 v[62:65], v[184:187], v[66:69], v[62:65]
	v_mfma_f32_16x16x32_bf16 v[62:65], v[188:191], v[70:73], v[62:65]
	v_mfma_f32_16x16x32_bf16 v[58:61], v[180:183], v[70:73], v[58:61]
	v_mfma_f32_16x16x32_bf16 v[58:61], v[192:195], v[66:69], v[58:61]
	v_mfma_f32_16x16x32_bf16 v[42:45], v[192:195], v[224:227], v[42:45]
	v_mfma_f32_16x16x32_bf16 v[42:45], v[180:183], v[228:231], v[42:45]
	v_mfma_f32_16x16x32_bf16 v[46:49], v[188:191], v[228:231], v[46:49]
	v_mfma_f32_16x16x32_bf16 v[46:49], v[184:187], v[224:227], v[46:49]
	v_mfma_f32_16x16x32_bf16 v[30:33], v[184:187], v[232:235], v[30:33]
	v_mfma_f32_16x16x32_bf16 v[30:33], v[188:191], v[240:243], v[30:33]
	v_mfma_f32_16x16x32_bf16 v[26:29], v[180:183], v[240:243], v[26:29]
	v_mfma_f32_16x16x32_bf16 v[26:29], v[192:195], v[232:235], v[26:29]
	v_mfma_f32_16x16x32_bf16 v[10:13], v[192:195], v[244:247], v[10:13]
	v_mfma_f32_16x16x32_bf16 v[10:13], v[180:183], v[248:251], v[10:13]
	v_mfma_f32_16x16x32_bf16 v[14:17], v[188:191], v[248:251], v[14:17]
	v_mfma_f32_16x16x32_bf16 v[14:17], v[184:187], v[244:247], v[14:17]
	s_setprio 0
	s_setprio 1
	s_and_b64 vcc, exec, s[82:83]
	s_cbranch_vccz .Lslv_b2
	v_mfma_f32_16x16x32_bf16 v[66:69], v[184:187], v[166:169], v[6:9]
	v_mfma_f32_16x16x32_bf16 v[70:73], v[192:195], v[166:169], v[2:5]
	v_mfma_f32_16x16x32_bf16 v[66:69], v[188:191], v[170:173], v[66:69]
	v_mfma_f32_16x16x32_bf16 v[70:73], v[180:183], v[170:173], v[70:73]
	s_branch .LBB0_815

; #define PG8_STAGE(bufoff, gbase, voff) do { _Pragma("unroll") for (int _i = 0; _i < 2; ++_i) \
;         __builtin_amdgcn_global_load_lds((const unsigned*)((const char*)(gbase) + (size_t)_i * qstep + (voff)[0]), (PG8_LAS unsigned*)(lds + (bufoff) + ldsw + _i * 8192), 16, 0, 0); } while (0)
; #define PG8_LDA(dst, b, h) do { _Pragma("unroll") for (int m = 0; m < 4; ++m) _Pragma("unroll") for (int k = 0; k < 2; ++k) dst[m][k] = *(const PG8_LAS bf16x8*)(lds + PG8_SA(b, h) + aoff + m * 2048 + k * 1024); } while (0)
; #define PG8_LDB(dst, b, h) do { _Pragma("unroll") for (int n = 0; n < 2; ++n) _Pragma("unroll") for (int k = 0; k < 2; ++k) dst[n][k] = *(const PG8_LAS bf16x8*)(lds + PG8_SB(b, h) + boff + n * 2048 + k * 1024); } while (0)
; #define PG8_WAIT_V89() do { if constexpr (SLIVER) PG8_WAIT_V(9); else PG8_WAIT_V(8); } while (0)
; #define PG8_WAIT_L(n) asm volatile("s_waitcnt lgkmcnt(" #n ")" ::: "memory")
; template <class Epi, class Sched, bool ALIGN_EPI = false, bool SP2 = false, bool SLIVER = false>
; __device__ __forceinline__ void gemm_phase(PG8_LAS unsigned char* lds, const Gemm g, const Sched& S, const Epi& E) {
;     ...
;         const bool has_next = S.next(ui + 1, nxt);
;         const char* nA = has_next ? (const char*)g.A + (size_t)nxt.pm * tstep + Epi::k0(nxt.seg) * 2 : cA; const char* nB = has_next ? (const char*)g.Bt + (size_t)nxt.pn * tstep + Epi::k0(nxt.seg) * 2 : cB;
;         const char* nS = has_next ? (const char*)g.A + (size_t)S.srow0 * K * 2 + (size_t)nxt.pm * sstep + Epi::k0(nxt.seg) * 2 : cS;
;         for (int t = 0; t < nt; t += 2) {
;             const bool last = (t == nt - 2);
;             const char* a1 = cA + (size_t)(t + 1) * kstep;
;             const char* a2 = last ? nA : cA + (size_t)(t + 2) * kstep; const char* b2 = last ? nB : cB + (size_t)(t + 2) * kstep;
;             const char* a3 = a2 + kstep; const char* b3 = b2 + kstep;
;             const char* s1 = cS + (size_t)(t + 1) * kstep; const char* s2 = last ? nS : cS + (size_t)(t + 2) * kstep;
;             if (last && has_next) S.a_ready(nxt);
;             if constexpr (SP2) {
;             PG8_LDB(B0, 0, 0); PG8_LDB(B1, 0, 1); PG8_SCHED; PG8_LDA(At, 0, 0); PG8_STAGE(PG8_SA(1, 1), a1 + hstep, voffA); PG8_STAGE_S(1, s1);
;             PG8_WAIT_V89(); PG8_WAIT_L(0); PG8_BAR; PG8_MMA(0, 0, At, B0); PG8_MMA(0, 1, At, B1); PG8_BAR; PG8_SCHED;
.LBB0_934:
	s_cmp_eq_u32 s66, s62
	s_cselect_b64 s[80:81], -1, 0
	s_add_u32 s12, s42, s62
	s_addc_u32 s13, s43, s63
	s_add_u32 s40, s12, 0x100
	s_addc_u32 s41, s13, 0
	s_and_b64 s[12:13], s[80:81], exec
	s_cselect_b32 s41, s95, s41
	s_cselect_b32 s40, s94, s40
	s_add_u32 s68, s17, s62
	s_addc_u32 s69, s45, s63
	s_add_i32 s76, 0, 0x10000
	s_and_b64 s[12:13], s[80:81], exec
	v_add_u32_e32 v138, s76, v212
	s_cselect_b32 s13, s97, s69
	s_cselect_b32 s12, s96, s68
	s_add_i32 s68, 0, 0x14000
	ds_read_b128 v[146:149], v138
	ds_read_b128 v[150:153], v138 offset:1024
	ds_read_b128 v[154:157], v138 offset:2048
	ds_read_b128 v[158:161], v138 offset:3072
	v_add_u32_e32 v138, s68, v212
	ds_read_b128 v[166:169], v138
	ds_read_b128 v[170:173], v138 offset:1024
	ds_read_b128 v[174:177], v138 offset:2048
	ds_read_b128 v[162:165], v138 offset:3072
	v_lshl_add_u64 v[202:203], v[198:199], 0, s[62:63]
	s_mov_b64 vcc, 0x90080
	v_lshl_add_u64 v[208:209], v[202:203], 0, vcc
	s_add_i32 m0, s93, 0xc000
	s_mov_b64 vcc, 0xd8080
	ds_read_b128 v[138:141], v215
	ds_read_b128 v[142:145], v215 offset:1024
	ds_read_b128 v[180:183], v215 offset:2048
	ds_read_b128 v[184:187], v215 offset:3072
	ds_read_b128 v[216:219], v215 offset:4096
	ds_read_b128 v[220:223], v215 offset:5120
	ds_read_b128 v[224:227], v215 offset:6144
	ds_read_b128 v[228:231], v215 offset:7168
	global_load_lds_dwordx4 v[208:209], off
	v_lshl_add_u64 v[202:203], v[202:203], 0, vcc
	s_add_i32 m0, s93, 0xe000
	s_nop 0
	global_load_lds_dwordx4 v[202:203], off
	v_lshl_add_u64 v[202:203], v[200:201], 0, s[62:63]
	s_add_i32 m0, s50, 0x20800
	s_nop 0
	global_load_lds_dword v[202:203], off
	s_waitcnt vmcnt(9)
	s_waitcnt lgkmcnt(0)
	s_setprio 1
	s_barrier
	v_mfma_f32_16x16x32_bf16 v[134:137], v[146:149], v[138:141], v[134:137]
	v_mfma_f32_16x16x32_bf16 v[134:137], v[150:153], v[142:145], v[134:137]
	v_mfma_f32_16x16x32_bf16 v[130:133], v[158:161], v[142:145], v[130:133]
	v_mfma_f32_16x16x32_bf16 v[130:133], v[154:157], v[138:141], v[130:133]
	v_mfma_f32_16x16x32_bf16 v[122:125], v[154:157], v[180:183], v[122:125]
	v_mfma_f32_16x16x32_bf16 v[122:125], v[158:161], v[184:187], v[122:125]
	v_mfma_f32_16x16x32_bf16 v[126:129], v[150:153], v[184:187], v[126:129]
	v_mfma_f32_16x16x32_bf16 v[126:129], v[146:149], v[180:183], v[126:129]
	v_mfma_f32_16x16x32_bf16 v[114:117], v[146:149], v[216:219], v[114:117]
	v_mfma_f32_16x16x32_bf16 v[114:117], v[150:153], v[220:223], v[114:117]
	v_mfma_f32_16x16x32_bf16 v[106:109], v[158:161], v[220:223], v[106:109]
	v_mfma_f32_16x16x32_bf16 v[106:109], v[154:157], v[216:219], v[106:109]
	v_mfma_f32_16x16x32_bf16 v[90:93], v[154:157], v[224:227], v[90:93]
	v_mfma_f32_16x16x32_bf16 v[90:93], v[158:161], v[228:231], v[90:93]
	v_mfma_f32_16x16x32_bf16 v[98:101], v[150:153], v[228:231], v[98:101]
	v_mfma_f32_16x16x32_bf16 v[98:101], v[146:149], v[224:227], v[98:101]
	s_setprio 0
	s_setprio 1
	v_mfma_f32_16x16x32_bf16 v[118:121], v[166:169], v[138:141], v[118:121]
	v_mfma_f32_16x16x32_bf16 v[118:121], v[170:173], v[142:145], v[118:121]
	v_mfma_f32_16x16x32_bf16 v[110:113], v[162:165], v[142:145], v[110:113]
	v_mfma_f32_16x16x32_bf16 v[110:113], v[174:177], v[138:141], v[110:113]
	v_mfma_f32_16x16x32_bf16 v[94:97], v[174:177], v[180:183], v[94:97]
	v_mfma_f32_16x16x32_bf16 v[94:97], v[162:165], v[184:187], v[94:97]
	v_mfma_f32_16x16x32_bf16 v[102:105], v[170:173], v[184:187], v[102:105]
	v_mfma_f32_16x16x32_bf16 v[102:105], v[166:169], v[180:183], v[102:105]
	v_mfma_f32_16x16x32_bf16 v[86:89], v[166:169], v[216:219], v[86:89]
	v_mfma_f32_16x16x32_bf16 v[86:89], v[170:173], v[220:223], v[86:89]
	v_mfma_f32_16x16x32_bf16 v[82:85], v[162:165], v[220:223], v[82:85]
	v_mfma_f32_16x16x32_bf16 v[82:85], v[174:177], v[216:219], v[82:85]
	v_mfma_f32_16x16x32_bf16 v[74:77], v[174:177], v[224:227], v[74:77]
	v_mfma_f32_16x16x32_bf16 v[74:77], v[162:165], v[228:231], v[74:77]
	v_mfma_f32_16x16x32_bf16 v[78:81], v[170:173], v[228:231], v[78:81]
	v_mfma_f32_16x16x32_bf16 v[78:81], v[166:169], v[224:227], v[78:81]
	s_barrier
; #define PG8_SB(B) __builtin_amdgcn_rcpf(1.f + expneg(B))
; #define PG8_SB(B) __builtin_amdgcn_rcpf(1.f + expneg(B))
; #define PG8_STAGE(bufoff, gbase, voff) do { _Pragma("unroll") for (int _i = 0; _i < 2; ++_i) \
;         __builtin_amdgcn_global_load_lds((const unsigned*)((const char*)(gbase) + (size_t)_i * qstep + (voff)[0]), (PG8_LAS unsigned*)(lds + (bufoff) + ldsw + _i * 8192), 16, 0, 0); } while (0)
; #define PG8_LDA(dst, b, h) do { _Pragma("unroll") for (int m = 0; m < 4; ++m) _Pragma("unroll") for (int k = 0; k < 2; ++k) dst[m][k] = *(const PG8_LAS bf16x8*)(lds + PG8_SA(b, h) + aoff + m * 2048 + k * 1024); } while (0)
; #define PG8_MMA(ai, bj, At, Bt) do { __builtin_amdgcn_s_setprio(1); _Pragma("unroll") for (int m = 0; m < 4; ++m) _Pragma("unroll") for (int n = 0; n < 2; ++n) _Pragma("unroll") for (int k = 0; k < 2; ++k) \
;         acc[ai][bj][m][n] = __builtin_amdgcn_mfma_f32_16x16x32_bf16(Bt[n][k], At[m][k], acc[ai][bj][m][n], 0, 0, 0); __builtin_amdgcn_s_setprio(0); } while (0)
; #define PG8_WAIT_V89() do { if constexpr (SLIVER) PG8_WAIT_V(9); else PG8_WAIT_V(8); } while (0)
; #define PG8_LDS_S(b) do { if constexpr (SLIVER) { Sf[0] = *(const PG8_LAS bf16x8*)(lds + STAGE_BYTES + (b) * 2048 + soff0); Sf[1] = *(const PG8_LAS bf16x8*)(lds + STAGE_BYTES + (b) * 2048 + (soff0 ^ 64)); } } while (0)
; #define PG8_WAIT_L(n) asm volatile("s_waitcnt lgkmcnt(" #n ")" ::: "memory")
; #define PG8_BAR __builtin_amdgcn_s_barrier()
; #define PG8_SCHED __builtin_amdgcn_sched_barrier(0)
; template <class Epi, class Sched, bool ALIGN_EPI = false, bool SP2 = false, bool SLIVER = false>
; __device__ __forceinline__ void gemm_phase(PG8_LAS unsigned char* lds, const Gemm g, const Sched& S, const Epi& E) {
;     ...
;             PG8_LDA(At, 0, 1); PG8_LDS_S(0); PG8_STAGE(PG8_SB(0, 0), b2, voffB); PG8_STAGE(PG8_SB(0, 1), b2 + hstep, voffB); PG8_STAGE(PG8_SA(0, 0), a2, voffA);
;             PG8_WAIT_V89(); PG8_WAIT_L(0); PG8_BAR; PG8_MMA(1, 0, At, B0); PG8_MMA(1, 1, At, B1); PG8_MMA_S(); PG8_BAR; PG8_SCHED;
	s_setprio 0
	s_add_i32 s69, 0, 0x20000
	v_lshl_add_u64 v[202:203], s[12:13], 0, v[190:191]
	s_add_i32 s12, s76, s92
	v_add_u32_e32 v178, s69, v213
	v_add_u32_e32 v184, s69, v214
	s_mov_b32 m0, s12
	ds_read_b128 v[138:141], v215 offset:16384
	ds_read_b128 v[142:145], v215 offset:17408
	ds_read_b128 v[216:219], v215 offset:18432
	ds_read_b128 v[220:223], v215 offset:19456
	ds_read_b128 v[224:227], v215 offset:20480
	ds_read_b128 v[228:231], v215 offset:21504
	ds_read_b128 v[232:235], v215 offset:22528
	ds_read_b128 v[240:243], v215 offset:23552
	ds_read_b128 v[180:183], v178
	ds_read_b128 v[184:187], v184
	global_load_lds_dwordx4 v[202:203], off
	v_lshl_add_u64 v[208:209], v[202:203], 0, s[70:71]
	s_add_i32 m0, s12, 0x2000
	s_add_i32 s12, s68, s92
	global_load_lds_dwordx4 v[208:209], off
	v_lshl_add_u64 v[208:209], v[202:203], 0, s[46:47]
	s_mov_b32 m0, s12
	v_lshl_add_u64 v[210:211], s[40:41], 0, v[188:189]
	global_load_lds_dwordx4 v[208:209], off
	v_lshl_add_u64 v[208:209], v[202:203], 0, s[6:7]
	s_add_i32 m0, s12, 0x2000
	s_nop 0
	global_load_lds_dwordx4 v[208:209], off
	s_mov_b32 m0, s93
	v_lshl_add_u64 v[208:209], v[210:211], 0, s[70:71]
	global_load_lds_dwordx4 v[210:211], off
	s_mov_b32 m0, s48
	s_nop 0
	global_load_lds_dwordx4 v[208:209], off
	s_waitcnt vmcnt(9)
	s_waitcnt lgkmcnt(0)
	s_setprio 1
	s_barrier
	v_mfma_f32_16x16x32_bf16 v[70:73], v[146:149], v[138:141], v[70:73]
	v_mfma_f32_16x16x32_bf16 v[70:73], v[150:153], v[142:145], v[70:73]
	v_mfma_f32_16x16x32_bf16 v[66:69], v[158:161], v[142:145], v[66:69]
	v_mfma_f32_16x16x32_bf16 v[66:69], v[154:157], v[138:141], v[66:69]
	v_mfma_f32_16x16x32_bf16 v[58:61], v[154:157], v[216:219], v[58:61]
	v_mfma_f32_16x16x32_bf16 v[58:61], v[158:161], v[220:223], v[58:61]
	v_mfma_f32_16x16x32_bf16 v[62:65], v[150:153], v[220:223], v[62:65]
	v_mfma_f32_16x16x32_bf16 v[62:65], v[146:149], v[216:219], v[62:65]
	v_mfma_f32_16x16x32_bf16 v[50:53], v[146:149], v[224:227], v[50:53]
	v_mfma_f32_16x16x32_bf16 v[50:53], v[150:153], v[228:231], v[50:53]
	v_mfma_f32_16x16x32_bf16 v[42:45], v[158:161], v[228:231], v[42:45]
	v_mfma_f32_16x16x32_bf16 v[42:45], v[154:157], v[224:227], v[42:45]
	v_mfma_f32_16x16x32_bf16 v[26:29], v[154:157], v[232:235], v[26:29]
	v_mfma_f32_16x16x32_bf16 v[26:29], v[158:161], v[240:243], v[26:29]
	v_mfma_f32_16x16x32_bf16 v[34:37], v[150:153], v[240:243], v[34:37]
	v_mfma_f32_16x16x32_bf16 v[34:37], v[146:149], v[232:235], v[34:37]
	s_setprio 0
	s_setprio 1
	v_mfma_f32_16x16x32_bf16 v[54:57], v[166:169], v[138:141], v[54:57]
	v_mfma_f32_16x16x32_bf16 v[54:57], v[170:173], v[142:145], v[54:57]
	v_mfma_f32_16x16x32_bf16 v[46:49], v[162:165], v[142:145], v[46:49]
	v_mfma_f32_16x16x32_bf16 v[46:49], v[174:177], v[138:141], v[46:49]
	v_mfma_f32_16x16x32_bf16 v[30:33], v[174:177], v[216:219], v[30:33]
	v_mfma_f32_16x16x32_bf16 v[30:33], v[162:165], v[220:223], v[30:33]
	v_mfma_f32_16x16x32_bf16 v[38:41], v[170:173], v[220:223], v[38:41]
	v_mfma_f32_16x16x32_bf16 v[38:41], v[166:169], v[216:219], v[38:41]
	v_mfma_f32_16x16x32_bf16 v[22:25], v[166:169], v[224:227], v[22:25]
	v_mfma_f32_16x16x32_bf16 v[22:25], v[170:173], v[228:231], v[22:25]
	v_mfma_f32_16x16x32_bf16 v[18:21], v[162:165], v[228:231], v[18:21]
	v_mfma_f32_16x16x32_bf16 v[18:21], v[174:177], v[224:227], v[18:21]
	v_mfma_f32_16x16x32_bf16 v[10:13], v[174:177], v[232:235], v[10:13]
	v_mfma_f32_16x16x32_bf16 v[10:13], v[162:165], v[240:243], v[10:13]
	v_mfma_f32_16x16x32_bf16 v[14:17], v[170:173], v[240:243], v[14:17]
	v_mfma_f32_16x16x32_bf16 v[14:17], v[166:169], v[232:235], v[14:17]
	s_setprio 0
	s_setprio 1
	s_and_b64 vcc, exec, s[90:91]
	s_cbranch_vccz .Lslv_b3
	v_mfma_f32_16x16x32_bf16 v[138:141], v[166:169], v[180:183], v[6:9]
	v_mfma_f32_16x16x32_bf16 v[142:145], v[174:177], v[180:183], v[2:5]
	v_mfma_f32_16x16x32_bf16 v[138:141], v[170:173], v[184:187], v[138:141]
	v_mfma_f32_16x16x32_bf16 v[142:145], v[162:165], v[184:187], v[142:145]
	s_branch .LBB0_938

; #define PG8_STAGE(bufoff, gbase, voff) do { _Pragma("unroll") for (int _i = 0; _i < 2; ++_i) \
;         __builtin_amdgcn_global_load_lds((const unsigned*)((const char*)(gbase) + (size_t)_i * qstep + (voff)[0]), (PG8_LAS unsigned*)(lds + (bufoff) + ldsw + _i * 8192), 16, 0, 0); } while (0)
; #define PG8_LDA(dst, b, h) do { _Pragma("unroll") for (int m = 0; m < 4; ++m) _Pragma("unroll") for (int k = 0; k < 2; ++k) dst[m][k] = *(const PG8_LAS bf16x8*)(lds + PG8_SA(b, h) + aoff + m * 2048 + k * 1024); } while (0)
; #define PG8_LDB(dst, b, h) do { _Pragma("unroll") for (int n = 0; n < 2; ++n) _Pragma("unroll") for (int k = 0; k < 2; ++k) dst[n][k] = *(const PG8_LAS bf16x8*)(lds + PG8_SB(b, h) + boff + n * 2048 + k * 1024); } while (0)
; #define PG8_MMA(ai, bj, At, Bt) do { __builtin_amdgcn_s_setprio(1); _Pragma("unroll") for (int m = 0; m < 4; ++m) _Pragma("unroll") for (int n = 0; n < 2; ++n) _Pragma("unroll") for (int k = 0; k < 2; ++k) \
;         acc[ai][bj][m][n] = __builtin_amdgcn_mfma_f32_16x16x32_bf16(Bt[n][k], At[m][k], acc[ai][bj][m][n], 0, 0, 0); __builtin_amdgcn_s_setprio(0); } while (0)
; #define PG8_WAIT_V89() do { if constexpr (SLIVER) PG8_WAIT_V(9); else PG8_WAIT_V(8); } while (0)
; #define PG8_STAGE_S(b, gbase) do { if constexpr (SLIVER) __builtin_amdgcn_global_load_lds((const unsigned*)((const char*)(gbase) + voffS), (PG8_LAS unsigned*)(lds + STAGE_BYTES + (b) * 2048 + wid * 256), 4, 0, 0); } while (0)
; #define PG8_WAIT_L(n) asm volatile("s_waitcnt lgkmcnt(" #n ")" ::: "memory")
; #define PG8_BAR __builtin_amdgcn_s_barrier()
; #define PG8_SCHED __builtin_amdgcn_sched_barrier(0)
; template <class Epi, class Sched, bool ALIGN_EPI = false, bool SP2 = false, bool SLIVER = false>
; __device__ __forceinline__ void gemm_phase(PG8_LAS unsigned char* lds, const Gemm g, const Sched& S, const Epi& E) {
;     ...
;             PG8_LDB(B0, 1, 0); PG8_LDB(B1, 1, 1); PG8_SCHED; PG8_LDA(At, 1, 0); PG8_STAGE(PG8_SA(0, 1), a2 + hstep, voffA); PG8_STAGE_S(0, s2);
;             PG8_WAIT_V89(); PG8_WAIT_L(0); PG8_BAR; PG8_MMA(0, 0, At, B0); PG8_MMA(0, 1, At, B1); PG8_BAR; PG8_SCHED;
.LBB0_938:
	s_barrier
	s_setprio 0
	s_add_u32 s12, s54, s62
	s_addc_u32 s13, s55, s63
	s_add_u32 s68, s12, 0x100
	s_addc_u32 s69, s13, 0
	s_and_b64 s[12:13], s[80:81], exec
	s_cselect_b32 s13, s19, s69
	s_cselect_b32 s12, s18, s68
	s_add_i32 s68, 0, 0x18000
	v_add_u32_e32 v2, s68, v212
	s_add_i32 s69, 0, 0x1c000
	ds_read_b128 v[146:149], v2
	ds_read_b128 v[150:153], v2 offset:1024
	ds_read_b128 v[154:157], v2 offset:2048
	ds_read_b128 v[158:161], v2 offset:3072
	v_add_u32_e32 v2, s69, v212
	ds_read_b128 v[166:169], v2
	ds_read_b128 v[170:173], v2 offset:1024
	ds_read_b128 v[174:177], v2 offset:2048
	ds_read_b128 v[162:165], v2 offset:3072
	s_mov_b32 m0, s49
	v_lshl_add_u64 v[208:209], v[210:211], 0, s[46:47]
	ds_read_b128 v[2:5], v215 offset:32768
	ds_read_b128 v[6:9], v215 offset:33792
	ds_read_b128 v[180:183], v215 offset:34816
	ds_read_b128 v[184:187], v215 offset:35840
	ds_read_b128 v[216:219], v215 offset:36864
	ds_read_b128 v[220:223], v215 offset:37888
	ds_read_b128 v[224:227], v215 offset:38912
	ds_read_b128 v[228:231], v215 offset:39936
	global_load_lds_dwordx4 v[208:209], off
	v_lshl_add_u64 v[208:209], v[210:211], 0, s[6:7]
	s_mov_b32 m0, s88
	s_nop 0
	global_load_lds_dwordx4 v[208:209], off
	v_lshl_add_u64 v[208:209], s[12:13], 0, v[192:193]
	s_mov_b32 m0, s89
	s_nop 0
	global_load_lds_dword v[208:209], off
	s_waitcnt vmcnt(9)
	s_waitcnt lgkmcnt(0)
	s_setprio 1
	s_barrier
	v_mfma_f32_16x16x32_bf16 v[134:137], v[146:149], v[2:5], v[134:137]
	v_mfma_f32_16x16x32_bf16 v[134:137], v[150:153], v[6:9], v[134:137]
	v_mfma_f32_16x16x32_bf16 v[130:133], v[158:161], v[6:9], v[130:133]
	v_mfma_f32_16x16x32_bf16 v[130:133], v[154:157], v[2:5], v[130:133]
	v_mfma_f32_16x16x32_bf16 v[122:125], v[154:157], v[180:183], v[122:125]
	v_mfma_f32_16x16x32_bf16 v[122:125], v[158:161], v[184:187], v[122:125]
	v_mfma_f32_16x16x32_bf16 v[126:129], v[150:153], v[184:187], v[126:129]
	v_mfma_f32_16x16x32_bf16 v[126:129], v[146:149], v[180:183], v[126:129]
	v_mfma_f32_16x16x32_bf16 v[114:117], v[146:149], v[216:219], v[114:117]
	v_mfma_f32_16x16x32_bf16 v[114:117], v[150:153], v[220:223], v[114:117]
	v_mfma_f32_16x16x32_bf16 v[106:109], v[158:161], v[220:223], v[106:109]
	v_mfma_f32_16x16x32_bf16 v[106:109], v[154:157], v[216:219], v[106:109]
	v_mfma_f32_16x16x32_bf16 v[90:93], v[154:157], v[224:227], v[90:93]
	v_mfma_f32_16x16x32_bf16 v[90:93], v[158:161], v[228:231], v[90:93]
	v_mfma_f32_16x16x32_bf16 v[98:101], v[150:153], v[228:231], v[98:101]
	v_mfma_f32_16x16x32_bf16 v[98:101], v[146:149], v[224:227], v[98:101]
	s_setprio 0
	s_setprio 1
	v_mfma_f32_16x16x32_bf16 v[118:121], v[166:169], v[2:5], v[118:121]
	v_mfma_f32_16x16x32_bf16 v[118:121], v[170:173], v[6:9], v[118:121]
	v_mfma_f32_16x16x32_bf16 v[2:5], v[174:177], v[2:5], v[110:113]
	v_mfma_f32_16x16x32_bf16 v[110:113], v[162:165], v[6:9], v[2:5]
	v_mfma_f32_16x16x32_bf16 v[2:5], v[166:169], v[180:183], v[102:105]
	v_mfma_f32_16x16x32_bf16 v[102:105], v[170:173], v[184:187], v[2:5]
	v_mfma_f32_16x16x32_bf16 v[2:5], v[174:177], v[180:183], v[94:97]
	v_mfma_f32_16x16x32_bf16 v[94:97], v[162:165], v[184:187], v[2:5]
	v_mfma_f32_16x16x32_bf16 v[2:5], v[166:169], v[216:219], v[86:89]
	v_mfma_f32_16x16x32_bf16 v[86:89], v[170:173], v[220:223], v[2:5]
	v_mfma_f32_16x16x32_bf16 v[2:5], v[174:177], v[216:219], v[82:85]
	v_mfma_f32_16x16x32_bf16 v[82:85], v[162:165], v[220:223], v[2:5]
	v_mfma_f32_16x16x32_bf16 v[2:5], v[166:169], v[224:227], v[78:81]
	v_mfma_f32_16x16x32_bf16 v[78:81], v[170:173], v[228:231], v[2:5]
	v_mfma_f32_16x16x32_bf16 v[2:5], v[174:177], v[224:227], v[74:77]
	v_mfma_f32_16x16x32_bf16 v[74:77], v[162:165], v[228:231], v[2:5]
	s_barrier
; #define PG8_SB(B) __builtin_amdgcn_rcpf(1.f + expneg(B))
; #define PG8_SB(B) __builtin_amdgcn_rcpf(1.f + expneg(B))
; #define PG8_STAGE(bufoff, gbase, voff) do { _Pragma("unroll") for (int _i = 0; _i < 2; ++_i) \
;         __builtin_amdgcn_global_load_lds((const unsigned*)((const char*)(gbase) + (size_t)_i * qstep + (voff)[0]), (PG8_LAS unsigned*)(lds + (bufoff) + ldsw + _i * 8192), 16, 0, 0); } while (0)
; #define PG8_LDA(dst, b, h) do { _Pragma("unroll") for (int m = 0; m < 4; ++m) _Pragma("unroll") for (int k = 0; k < 2; ++k) dst[m][k] = *(const PG8_LAS bf16x8*)(lds + PG8_SA(b, h) + aoff + m * 2048 + k * 1024); } while (0)
; #define PG8_MMA(ai, bj, At, Bt) do { __builtin_amdgcn_s_setprio(1); _Pragma("unroll") for (int m = 0; m < 4; ++m) _Pragma("unroll") for (int n = 0; n < 2; ++n) _Pragma("unroll") for (int k = 0; k < 2; ++k) \
;         acc[ai][bj][m][n] = __builtin_amdgcn_mfma_f32_16x16x32_bf16(Bt[n][k], At[m][k], acc[ai][bj][m][n], 0, 0, 0); __builtin_amdgcn_s_setprio(0); } while (0)
; #define PG8_WAIT_V89() do { if constexpr (SLIVER) PG8_WAIT_V(9); else PG8_WAIT_V(8); } while (0)
; #define PG8_LDS_S(b) do { if constexpr (SLIVER) { Sf[0] = *(const PG8_LAS bf16x8*)(lds + STAGE_BYTES + (b) * 2048 + soff0); Sf[1] = *(const PG8_LAS bf16x8*)(lds + STAGE_BYTES + (b) * 2048 + (soff0 ^ 64)); } } while (0)
; #define PG8_WAIT_L(n) asm volatile("s_waitcnt lgkmcnt(" #n ")" ::: "memory")
; #define PG8_BAR __builtin_amdgcn_s_barrier()
; #define PG8_SCHED __builtin_amdgcn_sched_barrier(0)
; template <class Epi, class Sched, bool ALIGN_EPI = false, bool SP2 = false, bool SLIVER = false>
; __device__ __forceinline__ void gemm_phase(PG8_LAS unsigned char* lds, const Gemm g, const Sched& S, const Epi& E) {
;     ...
;             PG8_LDA(At, 1, 1); PG8_LDS_S(1); PG8_STAGE(PG8_SB(1, 0), b3, voffB); PG8_STAGE(PG8_SB(1, 1), b3 + hstep, voffB); PG8_STAGE(PG8_SA(1, 0), a3, voffA);
;             PG8_WAIT_V89(); PG8_WAIT_L(0); PG8_BAR; PG8_MMA(1, 0, At, B0); PG8_MMA(1, 1, At, B1); PG8_MMA_S(); PG8_BAR; PG8_SCHED;
	s_setprio 0
	s_add_i32 s12, 0, 0x20800
	v_add_u32_e32 v178, s12, v213
	v_add_u32_e32 v184, s12, v214
	s_add_i32 s12, s68, s92
	v_lshl_add_u64 v[208:209], v[202:203], 0, s[26:27]
	s_mov_b32 m0, s12
	ds_read_b128 v[2:5], v215 offset:49152
	ds_read_b128 v[6:9], v215 offset:50176
	ds_read_b128 v[216:219], v215 offset:51200
	ds_read_b128 v[220:223], v215 offset:52224
	ds_read_b128 v[224:227], v215 offset:53248
	ds_read_b128 v[228:231], v215 offset:54272
	ds_read_b128 v[232:235], v215 offset:55296
	ds_read_b128 v[240:243], v215 offset:56320
	ds_read_b128 v[180:183], v178
	ds_read_b128 v[184:187], v184
	global_load_lds_dwordx4 v[208:209], off
	v_lshl_add_u64 v[208:209], v[202:203], 0, s[58:59]
	s_add_i32 m0, s12, 0x2000
	s_mov_b64 s[12:13], 0x90080
	global_load_lds_dwordx4 v[208:209], off
	v_lshl_add_u64 v[208:209], v[202:203], 0, s[12:13]
	s_add_i32 s12, s69, s92
	s_mov_b32 m0, s12
	s_mov_b64 s[68:69], 0xd8080
	global_load_lds_dwordx4 v[208:209], off
	v_lshl_add_u64 v[202:203], v[202:203], 0, s[68:69]
	s_add_i32 m0, s12, 0x2000
	s_nop 0
	global_load_lds_dwordx4 v[202:203], off
	v_lshl_add_u64 v[202:203], v[210:211], 0, s[26:27]
	s_mov_b32 m0, s51
	s_nop 0
	global_load_lds_dwordx4 v[202:203], off
	v_lshl_add_u64 v[202:203], v[210:211], 0, s[58:59]
	s_mov_b32 m0, s53
	s_nop 0
	global_load_lds_dwordx4 v[202:203], off
	s_waitcnt vmcnt(9)
	s_waitcnt lgkmcnt(0)
	s_setprio 1
	s_barrier
	v_mfma_f32_16x16x32_bf16 v[70:73], v[146:149], v[2:5], v[70:73]
	v_mfma_f32_16x16x32_bf16 v[70:73], v[150:153], v[6:9], v[70:73]
	v_mfma_f32_16x16x32_bf16 v[66:69], v[158:161], v[6:9], v[66:69]
	v_mfma_f32_16x16x32_bf16 v[66:69], v[154:157], v[2:5], v[66:69]
	v_mfma_f32_16x16x32_bf16 v[58:61], v[154:157], v[216:219], v[58:61]
	v_mfma_f32_16x16x32_bf16 v[58:61], v[158:161], v[220:223], v[58:61]
	v_mfma_f32_16x16x32_bf16 v[62:65], v[150:153], v[220:223], v[62:65]
	v_mfma_f32_16x16x32_bf16 v[62:65], v[146:149], v[216:219], v[62:65]
	v_mfma_f32_16x16x32_bf16 v[50:53], v[146:149], v[224:227], v[50:53]
	v_mfma_f32_16x16x32_bf16 v[50:53], v[150:153], v[228:231], v[50:53]
	v_mfma_f32_16x16x32_bf16 v[42:45], v[158:161], v[228:231], v[42:45]
	v_mfma_f32_16x16x32_bf16 v[42:45], v[154:157], v[224:227], v[42:45]
	v_mfma_f32_16x16x32_bf16 v[26:29], v[154:157], v[232:235], v[26:29]
	v_mfma_f32_16x16x32_bf16 v[26:29], v[158:161], v[240:243], v[26:29]
	v_mfma_f32_16x16x32_bf16 v[34:37], v[150:153], v[240:243], v[34:37]
	v_mfma_f32_16x16x32_bf16 v[34:37], v[146:149], v[232:235], v[34:37]
	s_setprio 0
	s_setprio 1
	v_mfma_f32_16x16x32_bf16 v[54:57], v[166:169], v[2:5], v[54:57]
	v_mfma_f32_16x16x32_bf16 v[54:57], v[170:173], v[6:9], v[54:57]
	v_mfma_f32_16x16x32_bf16 v[2:5], v[174:177], v[2:5], v[46:49]
	v_mfma_f32_16x16x32_bf16 v[46:49], v[162:165], v[6:9], v[2:5]
	v_mfma_f32_16x16x32_bf16 v[2:5], v[166:169], v[216:219], v[38:41]
	v_mfma_f32_16x16x32_bf16 v[38:41], v[170:173], v[220:223], v[2:5]
	v_mfma_f32_16x16x32_bf16 v[2:5], v[174:177], v[216:219], v[30:33]
	v_mfma_f32_16x16x32_bf16 v[30:33], v[162:165], v[220:223], v[2:5]
	v_mfma_f32_16x16x32_bf16 v[2:5], v[166:169], v[224:227], v[22:25]
	v_mfma_f32_16x16x32_bf16 v[22:25], v[170:173], v[228:231], v[2:5]
	v_mfma_f32_16x16x32_bf16 v[2:5], v[174:177], v[224:227], v[18:21]
	v_mfma_f32_16x16x32_bf16 v[18:21], v[162:165], v[228:231], v[2:5]
	v_mfma_f32_16x16x32_bf16 v[2:5], v[166:169], v[232:235], v[14:17]
	v_mfma_f32_16x16x32_bf16 v[14:17], v[170:173], v[240:243], v[2:5]
	v_mfma_f32_16x16x32_bf16 v[2:5], v[174:177], v[232:235], v[10:13]
	v_mfma_f32_16x16x32_bf16 v[10:13], v[162:165], v[240:243], v[2:5]
	s_setprio 0
	s_setprio 1
	s_and_b64 vcc, exec, s[90:91]
	s_cbranch_vccz .Lslv_c3
	v_mfma_f32_16x16x32_bf16 v[2:5], v[166:169], v[180:183], v[138:141]
	v_mfma_f32_16x16x32_bf16 v[6:9], v[170:173], v[184:187], v[2:5]
	v_mfma_f32_16x16x32_bf16 v[2:5], v[174:177], v[180:183], v[142:145]
	v_mfma_f32_16x16x32_bf16 v[2:5], v[162:165], v[184:187], v[2:5]
	s_branch .LBB0_933
